# sp1 retkv item: K-rotation load groups 1..6 prefetched two groups ahead into buffer registers (addresses = group 0 + constant strides) instead of 8 serialized load->wait->compute groups
# baseline (speedup 1.0000x reference)
; #define LAS __attribute__((address_space(3)))
; __device__ __forceinline__ unsigned pk2(float lo, float hi) { unsigned r; asm("v_cvt_pk_bf16_f32 %0, %1, %2" : "=v"(r) : "v"(lo), "v"(hi)); return r; }
; __device__ __forceinline__ float bflo(unsigned u) { return __uint_as_float(u << 16); }
; __device__ __forceinline__ float bfhi(unsigned u) { return __uint_as_float(u & 0xffff0000u); }
; __device__ __forceinline__ float log2_gamma(int h) { return log2f(1.0f - exp2f(-5.0f - (float)h)); }
; template <bool SCALE>
; __device__ __forceinline__ void load_tile_T(const bf16_t* src, LAS bf16_t* T, int lane, float sc0, float scmul) {
;     const int cr = lane >> 3, dc = lane & 7;
;     u32x4 v[8];
; #pragma unroll
;     for (int i = 0; i < 8; ++i) v[i] = *(const u32x4*)(src + (size_t)(cr + 8 * i) * INWP + 8 * dc);
; #pragma unroll
;     for (int i = 0; i < 8; ++i) { const int row = cr + 8 * i; u32x4 w = v[i];
;         if (SCALE) { const float s = sc0 * __builtin_amdgcn_exp2f(scmul * (float)row);
;             w.x = pk2(bflo(w.x) * s, bfhi(w.x) * s); w.y = pk2(bflo(w.y) * s, bfhi(w.y) * s); w.z = pk2(bflo(w.z) * s, bfhi(w.z) * s); w.w = pk2(bflo(w.w) * s, bfhi(w.w) * s); }
;         LAS bf16_t* t = T + (8 * dc) * TLD + row;
;         t[0 * TLD] = (bf16_t)(w.x & 0xffff); t[1 * TLD] = (bf16_t)(w.x >> 16); t[2 * TLD] = (bf16_t)(w.y & 0xffff); t[3 * TLD] = (bf16_t)(w.y >> 16);
;         t[4 * TLD] = (bf16_t)(w.z & 0xffff); t[5 * TLD] = (bf16_t)(w.z >> 16); t[6 * TLD] = (bf16_t)(w.w & 0xffff); t[7 * TLD] = (bf16_t)(w.w >> 16); }
; }
; __device__ __forceinline__ void retkv_item(const bf16_t* hbuf, const float* rot, float* kvbuf, LAS bf16_t* wl, int item, int lane) {
;     const int bh = item / NCHUNK, n = item % NCHUNK, b = bh / 6, h = bh % 6; const size_t t0 = (size_t)b * SEQ + (size_t)n * 64;
;     LAS bf16_t* kT = wl; LAS bf16_t* vT = wl + 64 * TLD;
;     const float l2g = log2_gamma(h);
;     load_tile_T<true>(hbuf + t0 * INWP + C_RV + h * 64, vT, lane, exp2f(l2g * 63.f), -l2g);
.LBB0_341:
	s_ashr_i32 s37, s36, 31
	s_lshr_b32 s0, s37, 24
	s_add_i32 s0, s36, s0
	s_mul_hi_i32 s1, s36, 0x2aaaaaab
	s_ashr_i32 s15, s0, 8
	s_lshr_b32 s17, s1, 31
	s_ashr_i32 s1, s1, 8
	s_add_i32 s20, s1, s17
	s_mul_hi_i32 s1, s15, 0x2aaaaaab
	s_lshr_b32 s17, s1, 31
	s_add_i32 s1, s1, s17
	s_mul_i32 s1, s1, 6
	s_sub_i32 s26, s15, s1
	s_and_b32 s0, s0, 0xffffff00
	v_cvt_f32_i32_e32 v0, s26
	s_sub_i32 s0, s36, s0
	s_ashr_i32 s21, s20, 31
	s_ashr_i32 s1, s0, 31
	s_lshl_b64 s[20:21], s[20:21], 14
	s_lshl_b64 s[0:1], s[0:1], 6
	s_add_u32 s20, s20, s0
	v_sub_f32_e32 v0, 0xc0a00000, v0
	s_addc_u32 s17, s21, s1
	v_cmp_gt_f32_e64 s[0:1], s47, v0
	v_mov_b32_e32 v51, v33
	v_mov_b32_e32 v53, v33
	v_cndmask_b32_e64 v1, 0, v229, s[0:1]
	v_add_f32_e32 v0, v0, v1
	v_exp_f32_e32 v0, v0
	s_and_b64 s[0:1], s[0:1], exec
	s_cselect_b32 s0, 0xffffffc0, 0
	v_mov_b32_e32 v55, v33
	v_ldexp_f32 v0, v0, s0
	v_sub_f32_e32 v0, 1.0, v0
	v_cmp_gt_f32_e64 s[0:1], s33, v0
	s_and_b64 s[22:23], s[0:1], exec
	s_cselect_b32 s21, 32, 0
	v_ldexp_f32 v0, v0, s21
	v_log_f32_e32 v0, v0
	v_cndmask_b32_e64 v1, 0, v246, s[0:1]
	s_mul_i32 s0, s17, 0x1800
	s_mul_hi_u32 s1, s20, 0x1800
	s_add_i32 s1, s1, s0
	s_mul_i32 s0, s20, 0x1800
	s_add_u32 s21, s42, s0
	v_sub_f32_e32 v61, v0, v1
	s_addc_u32 s23, s43, s1
	s_lshl_b32 s0, s26, 6
	s_ashr_i32 s1, s0, 31
	v_mul_f32_e32 v0, 0x427c0000, v61
	s_lshl_b64 s[38:39], s[0:1], 1
	v_cmp_gt_f32_e64 s[0:1], s47, v0
	s_add_u32 s22, s21, s38
	s_addc_u32 s23, s23, s39
	v_cndmask_b32_e64 v0, 0, v229, s[0:1]
	v_fmac_f32_e32 v0, 0x427c0000, v61
	v_exp_f32_e32 v0, v0
	s_and_b64 s[0:1], s[0:1], exec
	s_cselect_b32 s0, 0xffffffc0, 0
	v_mov_b32_e32 v57, v33
	v_ldexp_f32 v74, v0, s0
	v_lshl_add_u64 v[0:1], s[22:23], 0, v[32:33]
	s_mov_b64 s[0:1], 0x1100
	v_lshl_add_u64 v[70:71], v[0:1], 0, s[0:1]
	v_lshl_add_u64 v[12:13], v[70:71], 0, v[50:51]
	global_load_dwordx4 v[0:3], v[12:13], off
	v_add_co_u32_e64 v4, s[0:1], s41, v12
	v_lshl_add_u64 v[16:17], v[70:71], 0, v[52:53]
	s_nop 0
	v_addc_co_u32_e64 v5, s[0:1], 0, v13, s[0:1]
	global_load_dwordx4 v[4:7], v[4:5], off
	v_add_co_u32_e64 v8, s[0:1], s40, v12
	global_load_dwordx4 v[16:19], v[16:17], off
	s_nop 0
	v_addc_co_u32_e64 v9, s[0:1], 0, v13, s[0:1]
	global_load_dwordx4 v[8:11], v[8:9], off
	v_add_co_u32_e64 v12, s[0:1], s44, v12
	v_lshl_add_u64 v[20:21], v[70:71], 0, v[54:55]
	s_nop 0
	v_addc_co_u32_e64 v13, s[0:1], 0, v13, s[0:1]
	global_load_dwordx4 v[12:15], v[12:13], off
	v_mul_f32_e64 v51, v25, -v61
	global_load_dwordx4 v[20:23], v[20:21], off
	v_exp_f32_e32 v51, v51
	v_lshl_add_u64 v[66:67], v[70:71], 0, v[56:57]
	global_load_dwordx4 v[66:69], v[66:67], off
	v_mov_b32_e32 v59, v33
	v_mul_f32_e32 v51, v74, v51
	v_lshl_add_u64 v[70:71], v[70:71], 0, v[58:59]
	global_load_dwordx4 v[70:73], v[70:71], off
	s_waitcnt vmcnt(7)
	v_lshlrev_b32_e32 v53, 16, v0
	v_and_b32_e32 v0, 0xffff0000, v0
	v_mul_f32_e32 v53, v51, v53
	v_mul_f32_e32 v0, v51, v0
	v_cvt_pk_bf16_f32 v0, v53, v0
	v_lshlrev_b32_e32 v53, 16, v1
	v_and_b32_e32 v1, 0xffff0000, v1
	v_mul_f32_e32 v53, v51, v53
	v_mul_f32_e32 v1, v51, v1
	v_cvt_pk_bf16_f32 v1, v53, v1
	v_lshlrev_b32_e32 v53, 16, v2
	v_and_b32_e32 v2, 0xffff0000, v2
	v_mul_f32_e32 v53, v51, v53
	v_mul_f32_e32 v2, v51, v2
	v_cvt_pk_bf16_f32 v2, v53, v2
	v_lshlrev_b32_e32 v53, 16, v3
	v_and_b32_e32 v3, 0xffff0000, v3
	v_mul_f32_e32 v3, v51, v3
	v_mul_f32_e32 v53, v51, v53
	v_cvt_pk_bf16_f32 v3, v53, v3
	ds_write_b16 v29, v0 offset:9216
	ds_write_b16_d16_hi v29, v0 offset:9360
	ds_write_b16 v29, v1 offset:9504
	ds_write_b16_d16_hi v29, v1 offset:9648
	ds_write_b16 v29, v2 offset:9792
	ds_write_b16_d16_hi v29, v2 offset:9936
	ds_write_b16 v29, v3 offset:10080
	ds_write_b16_d16_hi v29, v3 offset:10224
	v_mul_f32_e64 v0, v31, -v61
	v_exp_f32_e32 v0, v0
	s_waitcnt vmcnt(6)
	v_lshlrev_b32_e32 v1, 16, v4
	v_and_b32_e32 v2, 0xffff0000, v4
	v_and_b32_e32 v3, 0xffff0000, v5
	v_mul_f32_e32 v0, v74, v0
	v_mul_f32_e32 v1, v0, v1
	v_mul_f32_e32 v2, v0, v2
	v_cvt_pk_bf16_f32 v1, v1, v2
	v_lshlrev_b32_e32 v2, 16, v5
	v_mul_f32_e32 v2, v0, v2
	v_mul_f32_e32 v3, v0, v3
	v_cvt_pk_bf16_f32 v2, v2, v3
	v_lshlrev_b32_e32 v3, 16, v6
	v_and_b32_e32 v4, 0xffff0000, v6
	v_mul_f32_e32 v3, v0, v3
	v_mul_f32_e32 v4, v0, v4
	v_cvt_pk_bf16_f32 v3, v3, v4
	v_lshlrev_b32_e32 v4, 16, v7
	v_and_b32_e32 v5, 0xffff0000, v7
	v_mul_f32_e32 v4, v0, v4
	v_mul_f32_e32 v0, v0, v5
	v_cvt_pk_bf16_f32 v0, v4, v0
	ds_write_b16 v29, v1 offset:9232
	ds_write_b16_d16_hi v29, v1 offset:9376
	ds_write_b16 v29, v2 offset:9520
	ds_write_b16_d16_hi v29, v2 offset:9664
	ds_write_b16 v29, v3 offset:9808
	ds_write_b16_d16_hi v29, v3 offset:9952
	ds_write_b16 v29, v0 offset:10096
	ds_write_b16_d16_hi v29, v0 offset:10240
	v_mul_f32_e64 v0, v35, -v61
	v_exp_f32_e32 v0, v0
	s_waitcnt vmcnt(4)
	v_lshlrev_b32_e32 v1, 16, v8
	v_and_b32_e32 v2, 0xffff0000, v8
	v_and_b32_e32 v3, 0xffff0000, v9
	v_mul_f32_e32 v0, v74, v0
	v_mul_f32_e32 v1, v0, v1
	v_mul_f32_e32 v2, v0, v2
	v_cvt_pk_bf16_f32 v1, v1, v2
	v_lshlrev_b32_e32 v2, 16, v9
	v_mul_f32_e32 v2, v0, v2
	v_mul_f32_e32 v3, v0, v3
	v_cvt_pk_bf16_f32 v2, v2, v3
	v_lshlrev_b32_e32 v3, 16, v10
	v_and_b32_e32 v4, 0xffff0000, v10
	v_mul_f32_e32 v3, v0, v3
	v_mul_f32_e32 v4, v0, v4
	v_cvt_pk_bf16_f32 v3, v3, v4
	v_lshlrev_b32_e32 v4, 16, v11
	v_and_b32_e32 v5, 0xffff0000, v11
	v_mul_f32_e32 v4, v0, v4
	v_mul_f32_e32 v0, v0, v5
	v_cvt_pk_bf16_f32 v0, v4, v0
	ds_write_b16 v29, v1 offset:9248
	ds_write_b16_d16_hi v29, v1 offset:9392
	ds_write_b16 v29, v2 offset:9536
	ds_write_b16_d16_hi v29, v2 offset:9680
	ds_write_b16 v29, v3 offset:9824
	ds_write_b16_d16_hi v29, v3 offset:9968
	ds_write_b16 v29, v0 offset:10112
	ds_write_b16_d16_hi v29, v0 offset:10256
	v_mul_f32_e64 v0, v37, -v61
	v_exp_f32_e32 v0, v0
	s_waitcnt vmcnt(3)
; #define LAS __attribute__((address_space(3)))
; __device__ __forceinline__ unsigned pk2(float lo, float hi) { unsigned r; asm("v_cvt_pk_bf16_f32 %0, %1, %2" : "=v"(r) : "v"(lo), "v"(hi)); return r; }
; __device__ __forceinline__ float bflo(unsigned u) { return __uint_as_float(u << 16); }
; __device__ __forceinline__ float bfhi(unsigned u) { return __uint_as_float(u & 0xffff0000u); }
; template <bool SCALE>
; __device__ __forceinline__ void load_tile_T(const bf16_t* src, LAS bf16_t* T, int lane, float sc0, float scmul) {
;     const int cr = lane >> 3, dc = lane & 7;
;     u32x4 v[8];
; #pragma unroll
;     for (int i = 0; i < 8; ++i) v[i] = *(const u32x4*)(src + (size_t)(cr + 8 * i) * INWP + 8 * dc);
; #pragma unroll
;     for (int i = 0; i < 8; ++i) { const int row = cr + 8 * i; u32x4 w = v[i];
;         if (SCALE) { const float s = sc0 * __builtin_amdgcn_exp2f(scmul * (float)row);
;             w.x = pk2(bflo(w.x) * s, bfhi(w.x) * s); w.y = pk2(bflo(w.y) * s, bfhi(w.y) * s); w.z = pk2(bflo(w.z) * s, bfhi(w.z) * s); w.w = pk2(bflo(w.w) * s, bfhi(w.w) * s); }
;         LAS bf16_t* t = T + (8 * dc) * TLD + row;
;         t[0 * TLD] = (bf16_t)(w.x & 0xffff); t[1 * TLD] = (bf16_t)(w.x >> 16); t[2 * TLD] = (bf16_t)(w.y & 0xffff); t[3 * TLD] = (bf16_t)(w.y >> 16);
;         t[4 * TLD] = (bf16_t)(w.z & 0xffff); t[5 * TLD] = (bf16_t)(w.z >> 16); t[6 * TLD] = (bf16_t)(w.w & 0xffff); t[7 * TLD] = (bf16_t)(w.w >> 16); }
; __device__ __forceinline__ void retkv_item(const bf16_t* hbuf, const float* rot, float* kvbuf, LAS bf16_t* wl, int item, int lane) {
;     ...
;     { const int cr = lane >> 3, dc = lane & 7, fc = dc & 3;
; #pragma unroll
;       for (int i = 0; i < 8; ++i) { const int row = cr + 8 * i; const bf16_t* kp = hbuf + (t0 + row) * INWP + C_RK + h * 64;
;           const u32x4 x1 = *(const u32x4*)(kp + 8 * fc), x2 = *(const u32x4*)(kp + 32 + 8 * fc);
;           const int pos = n * 64 + row; u32x4 o1, o2;
;           rot8(x1, x2, rot + (size_t)pos * 32 + 8 * fc, rot + 16384 * 32 + (size_t)pos * 32 + 8 * fc, 0.125f, o1, o2);
	v_lshlrev_b32_e32 v1, 16, v12
	v_and_b32_e32 v2, 0xffff0000, v12
	v_and_b32_e32 v3, 0xffff0000, v13
	v_mul_f32_e32 v0, v74, v0
	v_mul_f32_e32 v1, v0, v1
	v_mul_f32_e32 v2, v0, v2
	v_cvt_pk_bf16_f32 v1, v1, v2
	v_lshlrev_b32_e32 v2, 16, v13
	v_mul_f32_e32 v2, v0, v2
	v_mul_f32_e32 v3, v0, v3
	v_cvt_pk_bf16_f32 v2, v2, v3
	v_lshlrev_b32_e32 v3, 16, v14
	v_and_b32_e32 v4, 0xffff0000, v14
	v_mul_f32_e32 v3, v0, v3
	v_mul_f32_e32 v4, v0, v4
	v_cvt_pk_bf16_f32 v3, v3, v4
	v_lshlrev_b32_e32 v4, 16, v15
	v_and_b32_e32 v5, 0xffff0000, v15
	v_mul_f32_e32 v4, v0, v4
	v_mul_f32_e32 v0, v0, v5
	v_cvt_pk_bf16_f32 v0, v4, v0
	ds_write_b16 v29, v1 offset:9264
	ds_write_b16_d16_hi v29, v1 offset:9408
	ds_write_b16 v29, v2 offset:9552
	ds_write_b16_d16_hi v29, v2 offset:9696
	ds_write_b16 v29, v3 offset:9840
	ds_write_b16_d16_hi v29, v3 offset:9984
	ds_write_b16 v29, v0 offset:10128
	ds_write_b16_d16_hi v29, v0 offset:10272
	v_mul_f32_e64 v0, v39, -v61
	v_exp_f32_e32 v0, v0
	v_lshlrev_b32_e32 v1, 16, v16
	v_and_b32_e32 v2, 0xffff0000, v16
	v_and_b32_e32 v3, 0xffff0000, v17
	v_mul_f32_e32 v0, v74, v0
	v_mul_f32_e32 v1, v0, v1
	v_mul_f32_e32 v2, v0, v2
	v_cvt_pk_bf16_f32 v1, v1, v2
	v_lshlrev_b32_e32 v2, 16, v17
	v_mul_f32_e32 v2, v0, v2
	v_mul_f32_e32 v3, v0, v3
	v_cvt_pk_bf16_f32 v2, v2, v3
	v_lshlrev_b32_e32 v3, 16, v18
	v_and_b32_e32 v4, 0xffff0000, v18
	v_mul_f32_e32 v3, v0, v3
	v_mul_f32_e32 v4, v0, v4
	v_cvt_pk_bf16_f32 v3, v3, v4
	v_lshlrev_b32_e32 v4, 16, v19
	v_and_b32_e32 v5, 0xffff0000, v19
	v_mul_f32_e32 v4, v0, v4
	v_mul_f32_e32 v0, v0, v5
	v_cvt_pk_bf16_f32 v0, v4, v0
	ds_write_b16 v29, v1 offset:9280
	ds_write_b16_d16_hi v29, v1 offset:9424
	ds_write_b16 v29, v2 offset:9568
	ds_write_b16_d16_hi v29, v2 offset:9712
	ds_write_b16 v29, v3 offset:9856
	ds_write_b16_d16_hi v29, v3 offset:10000
	ds_write_b16 v29, v0 offset:10144
	ds_write_b16_d16_hi v29, v0 offset:10288
	v_mul_f32_e64 v0, v41, -v61
	v_exp_f32_e32 v0, v0
	s_waitcnt vmcnt(2)
	v_lshlrev_b32_e32 v1, 16, v20
	v_and_b32_e32 v2, 0xffff0000, v20
	v_and_b32_e32 v3, 0xffff0000, v21
	v_mul_f32_e32 v0, v74, v0
	v_mul_f32_e32 v1, v0, v1
	v_mul_f32_e32 v2, v0, v2
	v_cvt_pk_bf16_f32 v1, v1, v2
	v_lshlrev_b32_e32 v2, 16, v21
	v_mul_f32_e32 v2, v0, v2
	v_mul_f32_e32 v3, v0, v3
	v_cvt_pk_bf16_f32 v2, v2, v3
	v_lshlrev_b32_e32 v3, 16, v22
	v_and_b32_e32 v4, 0xffff0000, v22
	v_mul_f32_e32 v3, v0, v3
	v_mul_f32_e32 v4, v0, v4
	v_cvt_pk_bf16_f32 v3, v3, v4
	v_lshlrev_b32_e32 v4, 16, v23
	v_and_b32_e32 v5, 0xffff0000, v23
	v_mul_f32_e32 v4, v0, v4
	v_mul_f32_e32 v0, v0, v5
	v_cvt_pk_bf16_f32 v0, v4, v0
	ds_write_b16 v29, v1 offset:9296
	ds_write_b16_d16_hi v29, v1 offset:9440
	ds_write_b16 v29, v2 offset:9584
	ds_write_b16_d16_hi v29, v2 offset:9728
	ds_write_b16 v29, v3 offset:9872
	ds_write_b16_d16_hi v29, v3 offset:10016
	ds_write_b16 v29, v0 offset:10160
	ds_write_b16_d16_hi v29, v0 offset:10304
	v_mul_f32_e64 v0, v43, -v61
	v_exp_f32_e32 v0, v0
	s_waitcnt vmcnt(1)
	v_lshlrev_b32_e32 v1, 16, v66
	v_and_b32_e32 v2, 0xffff0000, v66
	v_and_b32_e32 v3, 0xffff0000, v67
	v_mul_f32_e32 v0, v74, v0
	v_mul_f32_e32 v1, v0, v1
	v_mul_f32_e32 v2, v0, v2
	v_cvt_pk_bf16_f32 v1, v1, v2
	v_lshlrev_b32_e32 v2, 16, v67
	v_mul_f32_e32 v2, v0, v2
	v_mul_f32_e32 v3, v0, v3
	v_cvt_pk_bf16_f32 v2, v2, v3
	v_lshlrev_b32_e32 v3, 16, v68
	v_and_b32_e32 v4, 0xffff0000, v68
	v_mul_f32_e32 v3, v0, v3
	v_mul_f32_e32 v4, v0, v4
	v_cvt_pk_bf16_f32 v3, v3, v4
	v_lshlrev_b32_e32 v4, 16, v69
	v_and_b32_e32 v5, 0xffff0000, v69
	v_mul_f32_e32 v4, v0, v4
	v_mul_f32_e32 v0, v0, v5
	v_cvt_pk_bf16_f32 v0, v4, v0
	ds_write_b16 v29, v1 offset:9312
	ds_write_b16_d16_hi v29, v1 offset:9456
	ds_write_b16 v29, v2 offset:9600
	ds_write_b16_d16_hi v29, v2 offset:9744
	ds_write_b16 v29, v3 offset:9888
	ds_write_b16_d16_hi v29, v3 offset:10032
	ds_write_b16 v29, v0 offset:10176
	ds_write_b16_d16_hi v29, v0 offset:10320
	v_mul_f32_e64 v0, v62, -v61
	v_exp_f32_e32 v0, v0
	s_waitcnt vmcnt(0)
	v_lshlrev_b32_e32 v1, 16, v70
	v_and_b32_e32 v2, 0xffff0000, v70
	v_and_b32_e32 v3, 0xffff0000, v71
	v_mul_f32_e32 v0, v74, v0
	v_mul_f32_e32 v1, v0, v1
	v_mul_f32_e32 v2, v0, v2
	v_cvt_pk_bf16_f32 v1, v1, v2
	v_lshlrev_b32_e32 v2, 16, v71
	v_mul_f32_e32 v2, v0, v2
	v_mul_f32_e32 v3, v0, v3
	v_cvt_pk_bf16_f32 v2, v2, v3
	v_lshlrev_b32_e32 v3, 16, v72
	v_and_b32_e32 v4, 0xffff0000, v72
	v_mul_f32_e32 v3, v0, v3
	v_mul_f32_e32 v4, v0, v4
	v_cvt_pk_bf16_f32 v3, v3, v4
	v_lshlrev_b32_e32 v4, 16, v73
	v_and_b32_e32 v5, 0xffff0000, v73
	v_mul_f32_e32 v4, v0, v4
	v_mul_f32_e32 v0, v0, v5
	v_cvt_pk_bf16_f32 v0, v4, v0
	ds_write_b16 v29, v1 offset:9328
	ds_write_b16_d16_hi v29, v1 offset:9472
	ds_write_b16 v29, v2 offset:9616
	ds_write_b16_d16_hi v29, v2 offset:9760
	ds_write_b16 v29, v3 offset:9904
	ds_write_b16_d16_hi v29, v3 offset:10048
	ds_write_b16 v29, v0 offset:10192
	ds_write_b16_d16_hi v29, v0 offset:10336
	v_or_b32_e32 v0, s20, v24
	v_mov_b64_e32 v[2:3], s[42:43]
	v_mad_u64_u32 v[0:1], s[0:1], v0, s5, v[2:3]
	v_mad_i32_i24 v1, s17, v207, v1
	v_lshl_add_u64 v[0:1], v[0:1], 0, s[38:39]
	v_mov_b32_e32 v61, v33
	v_lshl_add_u64 v[0:1], v[0:1], 0, v[60:61]
	s_lshl_b32 s0, s15, 14
	v_mov_b64_e32 v[152:153], v[0:1]
	global_load_dwordx4 v[4:7], v[0:1], off offset:3584
	global_load_dwordx4 v[8:11], v[0:1], off offset:3648
	v_subrev_u32_e32 v0, s0, v63
	v_subrev_u32_e32 v12, 56, v0
	v_ashrrev_i32_e32 v13, 31, v12
	v_lshlrev_b64 v[12:13], 7, v[12:13]
	v_lshl_add_u64 v[16:17], v[44:45], 0, v[12:13]
	v_lshl_add_u64 v[66:67], v[46:47], 0, v[12:13]
	v_mov_b64_e32 v[154:155], v[16:17]
	global_load_dwordx4 v[12:15], v[16:17], off offset:16
	s_nop 0
	global_load_dwordx4 v[16:19], v[16:17], off
	s_nop 0
	v_mov_b64_e32 v[156:157], v[66:67]
	global_load_dwordx4 v[20:23], v[66:67], off offset:16
	s_nop 0
	global_load_dwordx4 v[66:69], v[66:67], off
	s_mov_b32 s98, 0xc000
	s_mov_b32 s99, 0
	v_lshl_add_u64 v[158:159], s[98:99], 0, v[152:153]
	global_load_dwordx4 v[92:95], v[158:159], off offset:3584
	global_load_dwordx4 v[96:99], v[158:159], off offset:3648
	global_load_dwordx4 v[100:103], v[154:155], off offset:1040
	global_load_dwordx4 v[104:107], v[154:155], off offset:1024
	global_load_dwordx4 v[108:111], v[156:157], off offset:1040
	global_load_dwordx4 v[112:115], v[156:157], off offset:1024
	s_mov_b32 s98, 0x18000
	s_mov_b32 s99, 0
	v_lshl_add_u64 v[158:159], s[98:99], 0, v[152:153]
	global_load_dwordx4 v[116:119], v[158:159], off offset:3584
	global_load_dwordx4 v[120:123], v[158:159], off offset:3648
	global_load_dwordx4 v[124:127], v[154:155], off offset:2064
	global_load_dwordx4 v[128:131], v[154:155], off offset:2048
	global_load_dwordx4 v[132:135], v[156:157], off offset:2064
	global_load_dwordx4 v[136:139], v[156:157], off offset:2048
	v_add_u32_e32 v63, s12, v63
	s_waitcnt vmcnt(17)
; #define LAS __attribute__((address_space(3)))
; __device__ __forceinline__ void retkv_item(const bf16_t* hbuf, const float* rot, float* kvbuf, LAS bf16_t* wl, int item, int lane) {
;     ...
;     { const int cr = lane >> 3, dc = lane & 7, fc = dc & 3;
; #pragma unroll
;       for (int i = 0; i < 8; ++i) { const int row = cr + 8 * i; const bf16_t* kp = hbuf + (t0 + row) * INWP + C_RK + h * 64;
;           const u32x4 x1 = *(const u32x4*)(kp + 8 * fc), x2 = *(const u32x4*)(kp + 32 + 8 * fc);
;           const int pos = n * 64 + row; u32x4 o1, o2;
;           rot8(x1, x2, rot + (size_t)pos * 32 + 8 * fc, rot + 16384 * 32 + (size_t)pos * 32 + 8 * fc, 0.125f, o1, o2);
;           const u32x4 w = dc < 4 ? o1 : o2;
;           LAS bf16_t* t = kT + (8 * dc) * TLD + row;
;           t[0 * TLD] = (bf16_t)(w.x & 0xffff); t[1 * TLD] = (bf16_t)(w.x >> 16); t[2 * TLD] = (bf16_t)(w.y & 0xffff); t[3 * TLD] = (bf16_t)(w.y >> 16);
;           t[4 * TLD] = (bf16_t)(w.z & 0xffff); t[5 * TLD] = (bf16_t)(w.z >> 16); t[6 * TLD] = (bf16_t)(w.w & 0xffff); t[7 * TLD] = (bf16_t)(w.w >> 16); } }
	v_lshlrev_b32_e32 v71, 16, v4
	s_waitcnt vmcnt(16)
	v_lshlrev_b32_e32 v70, 16, v8
	s_waitcnt vmcnt(14)
	v_mov_b32_e32 v73, v16
	s_waitcnt vmcnt(12)
	v_mov_b32_e32 v72, v66
	v_pk_mul_f32 v[72:73], v[72:73], v[70:71]
	s_nop 0
	v_sub_f32_e32 v1, v73, v72
	v_mov_b32_e32 v72, v16
	v_mov_b32_e32 v73, v66
	v_pk_mul_f32 v[70:71], v[72:73], v[70:71]
	v_mov_b32_e32 v66, v17
	v_add_f32_e32 v16, v70, v71
	v_mul_f32_e32 v51, 0x3e000000, v16
	v_and_b32_e32 v71, 0xffff0000, v4
	v_and_b32_e32 v70, 0xffff0000, v8
	v_mov_b32_e32 v16, v67
	v_pk_mul_f32 v[72:73], v[16:17], v[70:71]
	v_pk_mul_f32 v[16:17], v[66:67], v[70:71]
	v_sub_f32_e32 v4, v73, v72
	v_mul_f32_e32 v53, 0x3e000000, v4
	v_add_f32_e32 v4, v16, v17
	v_lshlrev_b32_e32 v17, 16, v5
	v_lshlrev_b32_e32 v16, 16, v9
	v_mov_b32_e32 v66, v68
	v_mov_b32_e32 v67, v18
	v_pk_mul_f32 v[66:67], v[66:67], v[16:17]
	v_mul_f32_e32 v55, 0x3e000000, v4
	v_sub_f32_e32 v4, v67, v66
	v_mov_b32_e32 v66, v18
	v_mov_b32_e32 v67, v68
	v_pk_mul_f32 v[16:17], v[66:67], v[16:17]
	v_mul_f32_e32 v57, 0x3e000000, v4
	v_add_f32_e32 v4, v16, v17
	v_mul_f32_e32 v16, 0x3e000000, v4
	v_and_b32_e32 v5, 0xffff0000, v5
	v_and_b32_e32 v4, 0xffff0000, v9
	v_mov_b32_e32 v18, v69
	v_mov_b32_e32 v68, v19
	v_pk_mul_f32 v[8:9], v[18:19], v[4:5]
	v_pk_mul_f32 v[4:5], v[68:69], v[4:5]
	v_sub_f32_e32 v8, v9, v8
	v_add_f32_e32 v4, v4, v5
	v_mul_f32_e32 v17, 0x3e000000, v8
	v_mul_f32_e32 v18, 0x3e000000, v4
	v_lshlrev_b32_e32 v5, 16, v6
	v_lshlrev_b32_e32 v4, 16, v10
	v_mov_b32_e32 v8, v20
	v_mov_b32_e32 v9, v12
	v_pk_mul_f32 v[8:9], v[8:9], v[4:5]
	v_mul_f32_e32 v1, 0x3e000000, v1
	v_sub_f32_e32 v8, v9, v8
	v_mul_f32_e32 v19, 0x3e000000, v8
	v_mov_b32_e32 v8, v12
	v_mov_b32_e32 v9, v20
	v_pk_mul_f32 v[4:5], v[8:9], v[4:5]
	v_mov_b32_e32 v12, v21
	v_add_f32_e32 v4, v4, v5
	v_mul_f32_e32 v59, 0x3e000000, v4
	v_and_b32_e32 v5, 0xffff0000, v6
	v_and_b32_e32 v4, 0xffff0000, v10
	v_mov_b32_e32 v20, v13
	v_pk_mul_f32 v[8:9], v[12:13], v[4:5]
	v_pk_mul_f32 v[4:5], v[20:21], v[4:5]
	v_sub_f32_e32 v6, v9, v8
	v_add_f32_e32 v4, v4, v5
	v_mul_f32_e32 v12, 0x3e000000, v4
	v_lshlrev_b32_e32 v5, 16, v7
	v_lshlrev_b32_e32 v4, 16, v11
	v_mov_b32_e32 v8, v22
	v_mov_b32_e32 v9, v14
	v_pk_mul_f32 v[8:9], v[8:9], v[4:5]
	v_mul_f32_e32 v10, 0x3e000000, v6
	v_sub_f32_e32 v6, v9, v8
	v_mov_b32_e32 v8, v14
	v_mov_b32_e32 v9, v22
	v_pk_mul_f32 v[4:5], v[8:9], v[4:5]
	v_mov_b32_e32 v14, v23
	v_add_f32_e32 v4, v4, v5
	v_mul_f32_e32 v8, 0x3e000000, v4
	v_and_b32_e32 v5, 0xffff0000, v7
	v_and_b32_e32 v4, 0xffff0000, v11
	v_mov_b32_e32 v22, v15
	v_mul_f32_e32 v13, 0x3e000000, v6
	v_pk_mul_f32 v[6:7], v[14:15], v[4:5]
	v_pk_mul_f32 v[4:5], v[22:23], v[4:5]
	v_sub_f32_e32 v6, v7, v6
	v_add_f32_e32 v4, v4, v5
	v_mul_f32_e32 v6, 0x3e000000, v6
	v_mul_f32_e32 v4, 0x3e000000, v4
	v_cvt_pk_bf16_f32 v1, v1, v53
	v_cvt_pk_bf16_f32 v5, v57, v17
	v_cvt_pk_bf16_f32 v6, v13, v6
	v_cvt_pk_bf16_f32 v9, v51, v55
	v_cvt_pk_bf16_f32 v4, v8, v4
	v_cvt_pk_bf16_f32 v7, v19, v10
	v_cvt_pk_bf16_f32 v10, v16, v18
	v_cvt_pk_bf16_f32 v11, v59, v12
	v_subrev_u32_e32 v12, 48, v0
	v_cndmask_b32_e32 v1, v9, v1, vcc
	v_cndmask_b32_e32 v4, v4, v6, vcc
	v_cndmask_b32_e32 v6, v11, v7, vcc
	v_cndmask_b32_e32 v5, v10, v5, vcc
	ds_write_b16 v29, v1
	ds_write_b16_d16_hi v29, v1 offset:144
	ds_write_b16 v29, v5 offset:288
	ds_write_b16_d16_hi v29, v5 offset:432
	ds_write_b16 v29, v6 offset:576
	ds_write_b16_d16_hi v29, v6 offset:720
	ds_write_b16 v29, v4 offset:864
	ds_write_b16_d16_hi v29, v4 offset:1008
	v_or_b32_e32 v1, s20, v26
	v_mad_u64_u32 v[4:5], s[0:1], v1, s5, v[2:3]
	v_mad_i32_i24 v5, s17, v207, v5
	v_ashrrev_i32_e32 v13, 31, v12
	v_lshl_add_u64 v[4:5], v[4:5], 0, s[38:39]
	v_lshlrev_b64 v[12:13], 7, v[12:13]
	v_lshl_add_u64 v[8:9], v[4:5], 0, v[60:61]
	v_lshl_add_u64 v[16:17], v[44:45], 0, v[12:13]
	v_lshl_add_u64 v[66:67], v[46:47], 0, v[12:13]
	s_waitcnt vmcnt(6)
	v_mov_b64_e32 v[4:5], v[92:93]
	v_mov_b64_e32 v[6:7], v[94:95]
	v_mov_b64_e32 v[8:9], v[96:97]
	v_mov_b64_e32 v[10:11], v[98:99]
	v_mov_b64_e32 v[12:13], v[100:101]
	v_mov_b64_e32 v[14:15], v[102:103]
	v_mov_b64_e32 v[16:17], v[104:105]
	v_mov_b64_e32 v[18:19], v[106:107]
	v_mov_b64_e32 v[20:21], v[108:109]
	v_mov_b64_e32 v[22:23], v[110:111]
	v_mov_b64_e32 v[66:67], v[112:113]
	v_mov_b64_e32 v[68:69], v[114:115]
	s_mov_b32 s98, 0x24000
	s_mov_b32 s99, 0
	v_lshl_add_u64 v[158:159], s[98:99], 0, v[152:153]
	global_load_dwordx4 v[92:95], v[158:159], off offset:3584
	global_load_dwordx4 v[96:99], v[158:159], off offset:3648
	global_load_dwordx4 v[100:103], v[154:155], off offset:3088
	global_load_dwordx4 v[104:107], v[154:155], off offset:3072
	global_load_dwordx4 v[108:111], v[156:157], off offset:3088
	global_load_dwordx4 v[112:115], v[156:157], off offset:3072
	v_lshlrev_b32_e32 v71, 16, v4
	v_lshlrev_b32_e32 v70, 16, v8
	v_mov_b32_e32 v72, v66
	v_mov_b32_e32 v73, v16
	v_pk_mul_f32 v[72:73], v[72:73], v[70:71]
	s_nop 0
	v_sub_f32_e32 v1, v73, v72
	v_mov_b32_e32 v72, v16
	v_mov_b32_e32 v73, v66
	v_pk_mul_f32 v[70:71], v[72:73], v[70:71]
	v_mov_b32_e32 v66, v17
	v_add_f32_e32 v16, v70, v71
	v_mul_f32_e32 v51, 0x3e000000, v16
	v_and_b32_e32 v71, 0xffff0000, v4
	v_and_b32_e32 v70, 0xffff0000, v8
	v_mov_b32_e32 v16, v67
	v_pk_mul_f32 v[72:73], v[16:17], v[70:71]
	v_pk_mul_f32 v[16:17], v[66:67], v[70:71]
	v_sub_f32_e32 v4, v73, v72
	v_mul_f32_e32 v53, 0x3e000000, v4
	v_add_f32_e32 v4, v16, v17
	v_lshlrev_b32_e32 v17, 16, v5
	v_lshlrev_b32_e32 v16, 16, v9
	v_mov_b32_e32 v66, v68
	v_mov_b32_e32 v67, v18
	v_pk_mul_f32 v[66:67], v[66:67], v[16:17]
	v_mul_f32_e32 v55, 0x3e000000, v4
	v_sub_f32_e32 v4, v67, v66
	v_mov_b32_e32 v66, v18
; #define LAS __attribute__((address_space(3)))
; __device__ __forceinline__ void retkv_item(const bf16_t* hbuf, const float* rot, float* kvbuf, LAS bf16_t* wl, int item, int lane) {
;     ...
;     { const int cr = lane >> 3, dc = lane & 7, fc = dc & 3;
; #pragma unroll
;       for (int i = 0; i < 8; ++i) { const int row = cr + 8 * i; const bf16_t* kp = hbuf + (t0 + row) * INWP + C_RK + h * 64;
;           const u32x4 x1 = *(const u32x4*)(kp + 8 * fc), x2 = *(const u32x4*)(kp + 32 + 8 * fc);
;           const int pos = n * 64 + row; u32x4 o1, o2;
;           rot8(x1, x2, rot + (size_t)pos * 32 + 8 * fc, rot + 16384 * 32 + (size_t)pos * 32 + 8 * fc, 0.125f, o1, o2);
;           const u32x4 w = dc < 4 ? o1 : o2;
;           LAS bf16_t* t = kT + (8 * dc) * TLD + row;
;           t[0 * TLD] = (bf16_t)(w.x & 0xffff); t[1 * TLD] = (bf16_t)(w.x >> 16); t[2 * TLD] = (bf16_t)(w.y & 0xffff); t[3 * TLD] = (bf16_t)(w.y >> 16);
;           t[4 * TLD] = (bf16_t)(w.z & 0xffff); t[5 * TLD] = (bf16_t)(w.z >> 16); t[6 * TLD] = (bf16_t)(w.w & 0xffff); t[7 * TLD] = (bf16_t)(w.w >> 16); } }
	v_mov_b32_e32 v67, v68
	v_pk_mul_f32 v[16:17], v[66:67], v[16:17]
	v_mul_f32_e32 v57, 0x3e000000, v4
	v_add_f32_e32 v4, v16, v17
	v_mul_f32_e32 v16, 0x3e000000, v4
	v_and_b32_e32 v5, 0xffff0000, v5
	v_and_b32_e32 v4, 0xffff0000, v9
	v_mov_b32_e32 v18, v69
	v_mov_b32_e32 v68, v19
	v_pk_mul_f32 v[8:9], v[18:19], v[4:5]
	v_pk_mul_f32 v[4:5], v[68:69], v[4:5]
	v_sub_f32_e32 v8, v9, v8
	v_add_f32_e32 v4, v4, v5
	v_mul_f32_e32 v17, 0x3e000000, v8
	v_mul_f32_e32 v18, 0x3e000000, v4
	v_lshlrev_b32_e32 v5, 16, v6
	v_lshlrev_b32_e32 v4, 16, v10
	v_mov_b32_e32 v8, v20
	v_mov_b32_e32 v9, v12
	v_pk_mul_f32 v[8:9], v[8:9], v[4:5]
	v_mul_f32_e32 v1, 0x3e000000, v1
	v_sub_f32_e32 v8, v9, v8
	v_mul_f32_e32 v19, 0x3e000000, v8
	v_mov_b32_e32 v8, v12
	v_mov_b32_e32 v9, v20
	v_pk_mul_f32 v[4:5], v[8:9], v[4:5]
	v_mov_b32_e32 v12, v21
	v_add_f32_e32 v4, v4, v5
	v_mul_f32_e32 v59, 0x3e000000, v4
	v_and_b32_e32 v5, 0xffff0000, v6
	v_and_b32_e32 v4, 0xffff0000, v10
	v_mov_b32_e32 v20, v13
	v_pk_mul_f32 v[8:9], v[12:13], v[4:5]
	v_pk_mul_f32 v[4:5], v[20:21], v[4:5]
	v_sub_f32_e32 v6, v9, v8
	v_add_f32_e32 v4, v4, v5
	v_mul_f32_e32 v12, 0x3e000000, v4
	v_lshlrev_b32_e32 v5, 16, v7
	v_lshlrev_b32_e32 v4, 16, v11
	v_mov_b32_e32 v8, v22
	v_mov_b32_e32 v9, v14
	v_pk_mul_f32 v[8:9], v[8:9], v[4:5]
	v_mul_f32_e32 v10, 0x3e000000, v6
	v_sub_f32_e32 v6, v9, v8
	v_mov_b32_e32 v8, v14
	v_mov_b32_e32 v9, v22
	v_pk_mul_f32 v[4:5], v[8:9], v[4:5]
	v_mov_b32_e32 v14, v23
	v_add_f32_e32 v4, v4, v5
	v_mul_f32_e32 v8, 0x3e000000, v4
	v_and_b32_e32 v5, 0xffff0000, v7
	v_and_b32_e32 v4, 0xffff0000, v11
	v_mov_b32_e32 v22, v15
	v_mul_f32_e32 v13, 0x3e000000, v6
	v_pk_mul_f32 v[6:7], v[14:15], v[4:5]
	v_pk_mul_f32 v[4:5], v[22:23], v[4:5]
	v_sub_f32_e32 v6, v7, v6
	v_add_f32_e32 v4, v4, v5
	v_mul_f32_e32 v6, 0x3e000000, v6
	v_mul_f32_e32 v4, 0x3e000000, v4
	v_cvt_pk_bf16_f32 v1, v1, v53
	v_cvt_pk_bf16_f32 v5, v57, v17
	v_cvt_pk_bf16_f32 v6, v13, v6
	v_cvt_pk_bf16_f32 v9, v51, v55
	v_cvt_pk_bf16_f32 v4, v8, v4
	v_cvt_pk_bf16_f32 v7, v19, v10
	v_cvt_pk_bf16_f32 v10, v16, v18
	v_cvt_pk_bf16_f32 v11, v59, v12
	v_subrev_u32_e32 v12, 40, v0
	v_cndmask_b32_e32 v1, v9, v1, vcc
	v_cndmask_b32_e32 v4, v4, v6, vcc
	v_cndmask_b32_e32 v6, v11, v7, vcc
	v_cndmask_b32_e32 v5, v10, v5, vcc
	ds_write_b16 v29, v1 offset:16
	ds_write_b16_d16_hi v29, v1 offset:160
	ds_write_b16 v29, v5 offset:304
	ds_write_b16_d16_hi v29, v5 offset:448
	ds_write_b16 v29, v6 offset:592
	ds_write_b16_d16_hi v29, v6 offset:736
	ds_write_b16 v29, v4 offset:880
	ds_write_b16_d16_hi v29, v4 offset:1024
	v_or_b32_e32 v1, s20, v28
	v_mad_u64_u32 v[4:5], s[0:1], v1, s5, v[2:3]
	v_mad_i32_i24 v5, s17, v207, v5
	v_ashrrev_i32_e32 v13, 31, v12
	v_lshl_add_u64 v[4:5], v[4:5], 0, s[38:39]
	v_lshlrev_b64 v[12:13], 7, v[12:13]
	v_lshl_add_u64 v[8:9], v[4:5], 0, v[60:61]
	v_lshl_add_u64 v[16:17], v[44:45], 0, v[12:13]
	v_lshl_add_u64 v[66:67], v[46:47], 0, v[12:13]
	s_waitcnt vmcnt(6)
	v_mov_b64_e32 v[4:5], v[116:117]
	v_mov_b64_e32 v[6:7], v[118:119]
	v_mov_b64_e32 v[8:9], v[120:121]
	v_mov_b64_e32 v[10:11], v[122:123]
	v_mov_b64_e32 v[12:13], v[124:125]
	v_mov_b64_e32 v[14:15], v[126:127]
	v_mov_b64_e32 v[16:17], v[128:129]
	v_mov_b64_e32 v[18:19], v[130:131]
	v_mov_b64_e32 v[20:21], v[132:133]
	v_mov_b64_e32 v[22:23], v[134:135]
	v_mov_b64_e32 v[66:67], v[136:137]
	v_mov_b64_e32 v[68:69], v[138:139]
	s_mov_b32 s98, 0x30000
	s_mov_b32 s99, 0
	v_lshl_add_u64 v[158:159], s[98:99], 0, v[152:153]
	global_load_dwordx4 v[116:119], v[158:159], off offset:3584
	global_load_dwordx4 v[120:123], v[158:159], off offset:3648
	s_mov_b32 s98, 0x1000
	v_lshl_add_u64 v[158:159], s[98:99], 0, v[154:155]
	global_load_dwordx4 v[124:127], v[158:159], off offset:16
	global_load_dwordx4 v[128:131], v[158:159], off
	v_lshl_add_u64 v[158:159], s[98:99], 0, v[156:157]
	global_load_dwordx4 v[132:135], v[158:159], off offset:16
	global_load_dwordx4 v[136:139], v[158:159], off
	v_lshlrev_b32_e32 v71, 16, v4
	v_lshlrev_b32_e32 v70, 16, v8
	v_mov_b32_e32 v72, v66
	v_mov_b32_e32 v73, v16
	v_pk_mul_f32 v[72:73], v[72:73], v[70:71]
	s_nop 0
	v_sub_f32_e32 v1, v73, v72
	v_mov_b32_e32 v72, v16
	v_mov_b32_e32 v73, v66
	v_pk_mul_f32 v[70:71], v[72:73], v[70:71]
	v_mov_b32_e32 v66, v17
	v_add_f32_e32 v16, v70, v71
	v_mul_f32_e32 v51, 0x3e000000, v16
	v_and_b32_e32 v71, 0xffff0000, v4
	v_and_b32_e32 v70, 0xffff0000, v8
	v_mov_b32_e32 v16, v67
	v_pk_mul_f32 v[72:73], v[16:17], v[70:71]
	v_pk_mul_f32 v[16:17], v[66:67], v[70:71]
	v_sub_f32_e32 v4, v73, v72
	v_mul_f32_e32 v53, 0x3e000000, v4
	v_add_f32_e32 v4, v16, v17
	v_lshlrev_b32_e32 v17, 16, v5
	v_lshlrev_b32_e32 v16, 16, v9
	v_mov_b32_e32 v66, v68
	v_mov_b32_e32 v67, v18
	v_pk_mul_f32 v[66:67], v[66:67], v[16:17]
	v_mul_f32_e32 v55, 0x3e000000, v4
	v_sub_f32_e32 v4, v67, v66
	v_mov_b32_e32 v66, v18
	v_mov_b32_e32 v67, v68
	v_pk_mul_f32 v[16:17], v[66:67], v[16:17]
	v_mul_f32_e32 v57, 0x3e000000, v4
	v_add_f32_e32 v4, v16, v17
	v_mul_f32_e32 v16, 0x3e000000, v4
	v_and_b32_e32 v5, 0xffff0000, v5
	v_and_b32_e32 v4, 0xffff0000, v9
	v_mov_b32_e32 v18, v69
	v_mov_b32_e32 v68, v19
	v_pk_mul_f32 v[8:9], v[18:19], v[4:5]
	v_pk_mul_f32 v[4:5], v[68:69], v[4:5]
	v_sub_f32_e32 v8, v9, v8
	v_add_f32_e32 v4, v4, v5
	v_mul_f32_e32 v17, 0x3e000000, v8
	v_mul_f32_e32 v18, 0x3e000000, v4
	v_lshlrev_b32_e32 v5, 16, v6
	v_lshlrev_b32_e32 v4, 16, v10
	v_mov_b32_e32 v8, v20
	v_mov_b32_e32 v9, v12
	v_pk_mul_f32 v[8:9], v[8:9], v[4:5]
	v_mul_f32_e32 v1, 0x3e000000, v1
	v_sub_f32_e32 v8, v9, v8
	v_mul_f32_e32 v19, 0x3e000000, v8
	v_mov_b32_e32 v8, v12
	v_mov_b32_e32 v9, v20
	v_pk_mul_f32 v[4:5], v[8:9], v[4:5]
	v_mov_b32_e32 v12, v21
; #define LAS __attribute__((address_space(3)))
; __device__ __forceinline__ void retkv_item(const bf16_t* hbuf, const float* rot, float* kvbuf, LAS bf16_t* wl, int item, int lane) {
;     ...
;     { const int cr = lane >> 3, dc = lane & 7, fc = dc & 3;
; #pragma unroll
;       for (int i = 0; i < 8; ++i) { const int row = cr + 8 * i; const bf16_t* kp = hbuf + (t0 + row) * INWP + C_RK + h * 64;
;           const u32x4 x1 = *(const u32x4*)(kp + 8 * fc), x2 = *(const u32x4*)(kp + 32 + 8 * fc);
;           const int pos = n * 64 + row; u32x4 o1, o2;
;           rot8(x1, x2, rot + (size_t)pos * 32 + 8 * fc, rot + 16384 * 32 + (size_t)pos * 32 + 8 * fc, 0.125f, o1, o2);
;           const u32x4 w = dc < 4 ? o1 : o2;
;           LAS bf16_t* t = kT + (8 * dc) * TLD + row;
;           t[0 * TLD] = (bf16_t)(w.x & 0xffff); t[1 * TLD] = (bf16_t)(w.x >> 16); t[2 * TLD] = (bf16_t)(w.y & 0xffff); t[3 * TLD] = (bf16_t)(w.y >> 16);
;           t[4 * TLD] = (bf16_t)(w.z & 0xffff); t[5 * TLD] = (bf16_t)(w.z >> 16); t[6 * TLD] = (bf16_t)(w.w & 0xffff); t[7 * TLD] = (bf16_t)(w.w >> 16); } }
	v_add_f32_e32 v4, v4, v5
	v_mul_f32_e32 v59, 0x3e000000, v4
	v_and_b32_e32 v5, 0xffff0000, v6
	v_and_b32_e32 v4, 0xffff0000, v10
	v_mov_b32_e32 v20, v13
	v_pk_mul_f32 v[8:9], v[12:13], v[4:5]
	v_pk_mul_f32 v[4:5], v[20:21], v[4:5]
	v_sub_f32_e32 v6, v9, v8
	v_add_f32_e32 v4, v4, v5
	v_mul_f32_e32 v12, 0x3e000000, v4
	v_lshlrev_b32_e32 v5, 16, v7
	v_lshlrev_b32_e32 v4, 16, v11
	v_mov_b32_e32 v8, v22
	v_mov_b32_e32 v9, v14
	v_pk_mul_f32 v[8:9], v[8:9], v[4:5]
	v_mul_f32_e32 v10, 0x3e000000, v6
	v_sub_f32_e32 v6, v9, v8
	v_mov_b32_e32 v8, v14
	v_mov_b32_e32 v9, v22
	v_pk_mul_f32 v[4:5], v[8:9], v[4:5]
	v_mov_b32_e32 v14, v23
	v_add_f32_e32 v4, v4, v5
	v_mul_f32_e32 v8, 0x3e000000, v4
	v_and_b32_e32 v5, 0xffff0000, v7
	v_and_b32_e32 v4, 0xffff0000, v11
	v_mov_b32_e32 v22, v15
	v_mul_f32_e32 v13, 0x3e000000, v6
	v_pk_mul_f32 v[6:7], v[14:15], v[4:5]
	v_pk_mul_f32 v[4:5], v[22:23], v[4:5]
	v_sub_f32_e32 v6, v7, v6
	v_add_f32_e32 v4, v4, v5
	v_mul_f32_e32 v6, 0x3e000000, v6
	v_mul_f32_e32 v4, 0x3e000000, v4
	v_cvt_pk_bf16_f32 v1, v1, v53
	v_cvt_pk_bf16_f32 v5, v57, v17
	v_cvt_pk_bf16_f32 v6, v13, v6
	v_cvt_pk_bf16_f32 v9, v51, v55
	v_cvt_pk_bf16_f32 v4, v8, v4
	v_cvt_pk_bf16_f32 v7, v19, v10
	v_cvt_pk_bf16_f32 v10, v16, v18
	v_cvt_pk_bf16_f32 v11, v59, v12
	v_subrev_u32_e32 v12, 32, v0
	v_cndmask_b32_e32 v1, v9, v1, vcc
	v_cndmask_b32_e32 v4, v4, v6, vcc
	v_cndmask_b32_e32 v6, v11, v7, vcc
	v_cndmask_b32_e32 v5, v10, v5, vcc
	ds_write_b16 v29, v1 offset:32
	ds_write_b16_d16_hi v29, v1 offset:176
	ds_write_b16 v29, v5 offset:320
	ds_write_b16_d16_hi v29, v5 offset:464
	ds_write_b16 v29, v6 offset:608
	ds_write_b16_d16_hi v29, v6 offset:752
	ds_write_b16 v29, v4 offset:896
	ds_write_b16_d16_hi v29, v4 offset:1040
	v_or_b32_e32 v1, s20, v30
	v_mad_u64_u32 v[4:5], s[0:1], v1, s5, v[2:3]
	v_mad_i32_i24 v5, s17, v207, v5
	v_ashrrev_i32_e32 v13, 31, v12
	v_lshl_add_u64 v[4:5], v[4:5], 0, s[38:39]
	v_lshlrev_b64 v[12:13], 7, v[12:13]
	v_lshl_add_u64 v[8:9], v[4:5], 0, v[60:61]
	v_lshl_add_u64 v[16:17], v[44:45], 0, v[12:13]
	v_lshl_add_u64 v[66:67], v[46:47], 0, v[12:13]
	s_waitcnt vmcnt(6)
	v_mov_b64_e32 v[4:5], v[92:93]
	v_mov_b64_e32 v[6:7], v[94:95]
	v_mov_b64_e32 v[8:9], v[96:97]
	v_mov_b64_e32 v[10:11], v[98:99]
	v_mov_b64_e32 v[12:13], v[100:101]
	v_mov_b64_e32 v[14:15], v[102:103]
	v_mov_b64_e32 v[16:17], v[104:105]
	v_mov_b64_e32 v[18:19], v[106:107]
	v_mov_b64_e32 v[20:21], v[108:109]
	v_mov_b64_e32 v[22:23], v[110:111]
	v_mov_b64_e32 v[66:67], v[112:113]
	v_mov_b64_e32 v[68:69], v[114:115]
	s_mov_b32 s98, 0x3c000
	s_mov_b32 s99, 0
	v_lshl_add_u64 v[158:159], s[98:99], 0, v[152:153]
	global_load_dwordx4 v[92:95], v[158:159], off offset:3584
	global_load_dwordx4 v[96:99], v[158:159], off offset:3648
	s_mov_b32 s98, 0x1400
	v_lshl_add_u64 v[158:159], s[98:99], 0, v[154:155]
	global_load_dwordx4 v[100:103], v[158:159], off offset:16
	global_load_dwordx4 v[104:107], v[158:159], off
	v_lshl_add_u64 v[158:159], s[98:99], 0, v[156:157]
	global_load_dwordx4 v[108:111], v[158:159], off offset:16
	global_load_dwordx4 v[112:115], v[158:159], off
	v_lshlrev_b32_e32 v71, 16, v4
	v_lshlrev_b32_e32 v70, 16, v8
	v_mov_b32_e32 v72, v66
	v_mov_b32_e32 v73, v16
	v_pk_mul_f32 v[72:73], v[72:73], v[70:71]
	s_nop 0
	v_sub_f32_e32 v1, v73, v72
	v_mov_b32_e32 v72, v16
	v_mov_b32_e32 v73, v66
	v_pk_mul_f32 v[70:71], v[72:73], v[70:71]
	v_mov_b32_e32 v66, v17
	v_add_f32_e32 v16, v70, v71
	v_mul_f32_e32 v51, 0x3e000000, v16
	v_and_b32_e32 v71, 0xffff0000, v4
	v_and_b32_e32 v70, 0xffff0000, v8
	v_mov_b32_e32 v16, v67
	v_pk_mul_f32 v[72:73], v[16:17], v[70:71]
	v_pk_mul_f32 v[16:17], v[66:67], v[70:71]
	v_sub_f32_e32 v4, v73, v72
	v_mul_f32_e32 v53, 0x3e000000, v4
	v_add_f32_e32 v4, v16, v17
	v_lshlrev_b32_e32 v17, 16, v5
	v_lshlrev_b32_e32 v16, 16, v9
	v_mov_b32_e32 v66, v68
	v_mov_b32_e32 v67, v18
	v_pk_mul_f32 v[66:67], v[66:67], v[16:17]
	v_mul_f32_e32 v55, 0x3e000000, v4
	v_sub_f32_e32 v4, v67, v66
	v_mov_b32_e32 v66, v18
	v_mov_b32_e32 v67, v68
	v_pk_mul_f32 v[16:17], v[66:67], v[16:17]
	v_mul_f32_e32 v57, 0x3e000000, v4
	v_add_f32_e32 v4, v16, v17
	v_mul_f32_e32 v16, 0x3e000000, v4
	v_and_b32_e32 v5, 0xffff0000, v5
	v_and_b32_e32 v4, 0xffff0000, v9
	v_mov_b32_e32 v18, v69
	v_mov_b32_e32 v68, v19
	v_pk_mul_f32 v[8:9], v[18:19], v[4:5]
	v_pk_mul_f32 v[4:5], v[68:69], v[4:5]
	v_sub_f32_e32 v8, v9, v8
	v_add_f32_e32 v4, v4, v5
	v_mul_f32_e32 v17, 0x3e000000, v8
	v_mul_f32_e32 v18, 0x3e000000, v4
	v_lshlrev_b32_e32 v5, 16, v6
	v_lshlrev_b32_e32 v4, 16, v10
	v_mov_b32_e32 v8, v20
	v_mov_b32_e32 v9, v12
	v_pk_mul_f32 v[8:9], v[8:9], v[4:5]
	v_mul_f32_e32 v1, 0x3e000000, v1
	v_sub_f32_e32 v8, v9, v8
	v_mul_f32_e32 v19, 0x3e000000, v8
	v_mov_b32_e32 v8, v12
	v_mov_b32_e32 v9, v20
	v_pk_mul_f32 v[4:5], v[8:9], v[4:5]
	v_mov_b32_e32 v12, v21
	v_add_f32_e32 v4, v4, v5
	v_mul_f32_e32 v59, 0x3e000000, v4
	v_and_b32_e32 v5, 0xffff0000, v6
	v_and_b32_e32 v4, 0xffff0000, v10
	v_mov_b32_e32 v20, v13
	v_pk_mul_f32 v[8:9], v[12:13], v[4:5]
	v_pk_mul_f32 v[4:5], v[20:21], v[4:5]
	v_sub_f32_e32 v6, v9, v8
	v_add_f32_e32 v4, v4, v5
	v_mul_f32_e32 v12, 0x3e000000, v4
	v_lshlrev_b32_e32 v5, 16, v7
	v_lshlrev_b32_e32 v4, 16, v11
	v_mov_b32_e32 v8, v22
	v_mov_b32_e32 v9, v14
	v_pk_mul_f32 v[8:9], v[8:9], v[4:5]
	v_mul_f32_e32 v10, 0x3e000000, v6
	v_sub_f32_e32 v6, v9, v8
	v_mov_b32_e32 v8, v14
	v_mov_b32_e32 v9, v22
	v_pk_mul_f32 v[4:5], v[8:9], v[4:5]
	v_mov_b32_e32 v14, v23
	v_add_f32_e32 v4, v4, v5
	v_mul_f32_e32 v8, 0x3e000000, v4
	v_and_b32_e32 v5, 0xffff0000, v7
	v_and_b32_e32 v4, 0xffff0000, v11
	v_mov_b32_e32 v22, v15
	v_mul_f32_e32 v13, 0x3e000000, v6
	v_pk_mul_f32 v[6:7], v[14:15], v[4:5]
	v_pk_mul_f32 v[4:5], v[22:23], v[4:5]
	v_sub_f32_e32 v6, v7, v6
	v_add_f32_e32 v4, v4, v5
	v_mul_f32_e32 v6, 0x3e000000, v6
	v_mul_f32_e32 v4, 0x3e000000, v4
	v_cvt_pk_bf16_f32 v1, v1, v53
	v_cvt_pk_bf16_f32 v5, v57, v17
	v_cvt_pk_bf16_f32 v6, v13, v6
	v_cvt_pk_bf16_f32 v9, v51, v55
	v_cvt_pk_bf16_f32 v4, v8, v4
	v_cvt_pk_bf16_f32 v7, v19, v10
	v_cvt_pk_bf16_f32 v10, v16, v18
	v_cvt_pk_bf16_f32 v11, v59, v12
	v_subrev_u32_e32 v12, 24, v0
	v_cndmask_b32_e32 v1, v9, v1, vcc
	v_cndmask_b32_e32 v4, v4, v6, vcc
	v_cndmask_b32_e32 v6, v11, v7, vcc
	v_cndmask_b32_e32 v5, v10, v5, vcc
	ds_write_b16 v29, v1 offset:48
	ds_write_b16_d16_hi v29, v1 offset:192
	ds_write_b16 v29, v5 offset:336
	ds_write_b16_d16_hi v29, v5 offset:480
	ds_write_b16 v29, v6 offset:624
	ds_write_b16_d16_hi v29, v6 offset:768
	ds_write_b16 v29, v4 offset:912
	ds_write_b16_d16_hi v29, v4 offset:1056
	v_or_b32_e32 v1, s20, v34
	v_mad_u64_u32 v[4:5], s[0:1], v1, s5, v[2:3]
	v_mad_i32_i24 v5, s17, v207, v5
	v_ashrrev_i32_e32 v13, 31, v12
	v_lshl_add_u64 v[4:5], v[4:5], 0, s[38:39]
	v_lshlrev_b64 v[12:13], 7, v[12:13]
	v_lshl_add_u64 v[8:9], v[4:5], 0, v[60:61]
	v_lshl_add_u64 v[16:17], v[44:45], 0, v[12:13]
	v_lshl_add_u64 v[66:67], v[46:47], 0, v[12:13]
	s_waitcnt vmcnt(6)
; #define LAS __attribute__((address_space(3)))
; __device__ __forceinline__ void retkv_item(const bf16_t* hbuf, const float* rot, float* kvbuf, LAS bf16_t* wl, int item, int lane) {
;     ...
;     { const int cr = lane >> 3, dc = lane & 7, fc = dc & 3;
; #pragma unroll
;       for (int i = 0; i < 8; ++i) { const int row = cr + 8 * i; const bf16_t* kp = hbuf + (t0 + row) * INWP + C_RK + h * 64;
;           const u32x4 x1 = *(const u32x4*)(kp + 8 * fc), x2 = *(const u32x4*)(kp + 32 + 8 * fc);
;           const int pos = n * 64 + row; u32x4 o1, o2;
;           rot8(x1, x2, rot + (size_t)pos * 32 + 8 * fc, rot + 16384 * 32 + (size_t)pos * 32 + 8 * fc, 0.125f, o1, o2);
;           const u32x4 w = dc < 4 ? o1 : o2;
;           LAS bf16_t* t = kT + (8 * dc) * TLD + row;
;           t[0 * TLD] = (bf16_t)(w.x & 0xffff); t[1 * TLD] = (bf16_t)(w.x >> 16); t[2 * TLD] = (bf16_t)(w.y & 0xffff); t[3 * TLD] = (bf16_t)(w.y >> 16);
;           t[4 * TLD] = (bf16_t)(w.z & 0xffff); t[5 * TLD] = (bf16_t)(w.z >> 16); t[6 * TLD] = (bf16_t)(w.w & 0xffff); t[7 * TLD] = (bf16_t)(w.w >> 16); } }
	v_mov_b64_e32 v[4:5], v[116:117]
	v_mov_b64_e32 v[6:7], v[118:119]
	v_mov_b64_e32 v[8:9], v[120:121]
	v_mov_b64_e32 v[10:11], v[122:123]
	v_mov_b64_e32 v[12:13], v[124:125]
	v_mov_b64_e32 v[14:15], v[126:127]
	v_mov_b64_e32 v[16:17], v[128:129]
	v_mov_b64_e32 v[18:19], v[130:131]
	v_mov_b64_e32 v[20:21], v[132:133]
	v_mov_b64_e32 v[22:23], v[134:135]
	v_mov_b64_e32 v[66:67], v[136:137]
	v_mov_b64_e32 v[68:69], v[138:139]
	s_mov_b32 s98, 0x48000
	s_mov_b32 s99, 0
	v_lshl_add_u64 v[158:159], s[98:99], 0, v[152:153]
	global_load_dwordx4 v[116:119], v[158:159], off offset:3584
	global_load_dwordx4 v[120:123], v[158:159], off offset:3648
	s_mov_b32 s98, 0x1800
	v_lshl_add_u64 v[158:159], s[98:99], 0, v[154:155]
	global_load_dwordx4 v[124:127], v[158:159], off offset:16
	global_load_dwordx4 v[128:131], v[158:159], off
	v_lshl_add_u64 v[158:159], s[98:99], 0, v[156:157]
	global_load_dwordx4 v[132:135], v[158:159], off offset:16
	global_load_dwordx4 v[136:139], v[158:159], off
	v_lshlrev_b32_e32 v71, 16, v4
	v_lshlrev_b32_e32 v70, 16, v8
	v_mov_b32_e32 v72, v66
	v_mov_b32_e32 v73, v16
	v_pk_mul_f32 v[72:73], v[72:73], v[70:71]
	s_nop 0
	v_sub_f32_e32 v1, v73, v72
	v_mov_b32_e32 v72, v16
	v_mov_b32_e32 v73, v66
	v_pk_mul_f32 v[70:71], v[72:73], v[70:71]
	v_mov_b32_e32 v66, v17
	v_add_f32_e32 v16, v70, v71
	v_mul_f32_e32 v51, 0x3e000000, v16
	v_and_b32_e32 v71, 0xffff0000, v4
	v_and_b32_e32 v70, 0xffff0000, v8
	v_mov_b32_e32 v16, v67
	v_pk_mul_f32 v[72:73], v[16:17], v[70:71]
	v_pk_mul_f32 v[16:17], v[66:67], v[70:71]
	v_sub_f32_e32 v4, v73, v72
	v_mul_f32_e32 v53, 0x3e000000, v4
	v_add_f32_e32 v4, v16, v17
	v_lshlrev_b32_e32 v17, 16, v5
	v_lshlrev_b32_e32 v16, 16, v9
	v_mov_b32_e32 v66, v68
	v_mov_b32_e32 v67, v18
	v_pk_mul_f32 v[66:67], v[66:67], v[16:17]
	v_mul_f32_e32 v55, 0x3e000000, v4
	v_sub_f32_e32 v4, v67, v66
	v_mov_b32_e32 v66, v18
	v_mov_b32_e32 v67, v68
	v_pk_mul_f32 v[16:17], v[66:67], v[16:17]
	v_mul_f32_e32 v57, 0x3e000000, v4
	v_add_f32_e32 v4, v16, v17
	v_mul_f32_e32 v16, 0x3e000000, v4
	v_and_b32_e32 v5, 0xffff0000, v5
	v_and_b32_e32 v4, 0xffff0000, v9
	v_mov_b32_e32 v18, v69
	v_mov_b32_e32 v68, v19
	v_pk_mul_f32 v[8:9], v[18:19], v[4:5]
	v_pk_mul_f32 v[4:5], v[68:69], v[4:5]
	v_sub_f32_e32 v8, v9, v8
	v_add_f32_e32 v4, v4, v5
	v_mul_f32_e32 v17, 0x3e000000, v8
	v_mul_f32_e32 v18, 0x3e000000, v4
	v_lshlrev_b32_e32 v5, 16, v6
	v_lshlrev_b32_e32 v4, 16, v10
	v_mov_b32_e32 v8, v20
	v_mov_b32_e32 v9, v12
	v_pk_mul_f32 v[8:9], v[8:9], v[4:5]
	v_mul_f32_e32 v1, 0x3e000000, v1
	v_sub_f32_e32 v8, v9, v8
	v_mul_f32_e32 v19, 0x3e000000, v8
	v_mov_b32_e32 v8, v12
	v_mov_b32_e32 v9, v20
	v_pk_mul_f32 v[4:5], v[8:9], v[4:5]
	v_mov_b32_e32 v12, v21
	v_add_f32_e32 v4, v4, v5
	v_mul_f32_e32 v59, 0x3e000000, v4
	v_and_b32_e32 v5, 0xffff0000, v6
	v_and_b32_e32 v4, 0xffff0000, v10
	v_mov_b32_e32 v20, v13
	v_pk_mul_f32 v[8:9], v[12:13], v[4:5]
	v_pk_mul_f32 v[4:5], v[20:21], v[4:5]
	v_sub_f32_e32 v6, v9, v8
	v_add_f32_e32 v4, v4, v5
	v_mul_f32_e32 v12, 0x3e000000, v4
	v_lshlrev_b32_e32 v5, 16, v7
	v_lshlrev_b32_e32 v4, 16, v11
	v_mov_b32_e32 v8, v22
	v_mov_b32_e32 v9, v14
	v_pk_mul_f32 v[8:9], v[8:9], v[4:5]
	v_mul_f32_e32 v10, 0x3e000000, v6
	v_sub_f32_e32 v6, v9, v8
	v_mov_b32_e32 v8, v14
	v_mov_b32_e32 v9, v22
	v_pk_mul_f32 v[4:5], v[8:9], v[4:5]
	v_mov_b32_e32 v14, v23
	v_add_f32_e32 v4, v4, v5
	v_mul_f32_e32 v8, 0x3e000000, v4
	v_and_b32_e32 v5, 0xffff0000, v7
	v_and_b32_e32 v4, 0xffff0000, v11
	v_mov_b32_e32 v22, v15
	v_mul_f32_e32 v13, 0x3e000000, v6
	v_pk_mul_f32 v[6:7], v[14:15], v[4:5]
	v_pk_mul_f32 v[4:5], v[22:23], v[4:5]
	v_sub_f32_e32 v6, v7, v6
	v_add_f32_e32 v4, v4, v5
	v_mul_f32_e32 v6, 0x3e000000, v6
	v_mul_f32_e32 v4, 0x3e000000, v4
	v_cvt_pk_bf16_f32 v1, v1, v53
	v_cvt_pk_bf16_f32 v5, v57, v17
	v_cvt_pk_bf16_f32 v6, v13, v6
	v_cvt_pk_bf16_f32 v9, v51, v55
	v_cvt_pk_bf16_f32 v4, v8, v4
	v_cvt_pk_bf16_f32 v7, v19, v10
	v_cvt_pk_bf16_f32 v10, v16, v18
	v_cvt_pk_bf16_f32 v11, v59, v12
	v_add_u32_e32 v12, -16, v0
	v_cndmask_b32_e32 v1, v9, v1, vcc
	v_cndmask_b32_e32 v4, v4, v6, vcc
	v_cndmask_b32_e32 v6, v11, v7, vcc
	v_cndmask_b32_e32 v5, v10, v5, vcc
	ds_write_b16 v29, v1 offset:64
	ds_write_b16_d16_hi v29, v1 offset:208
	ds_write_b16 v29, v5 offset:352
	ds_write_b16_d16_hi v29, v5 offset:496
	ds_write_b16 v29, v6 offset:640
	ds_write_b16_d16_hi v29, v6 offset:784
	ds_write_b16 v29, v4 offset:928
	ds_write_b16_d16_hi v29, v4 offset:1072
	v_or_b32_e32 v1, s20, v36
	v_mad_u64_u32 v[4:5], s[0:1], v1, s5, v[2:3]
	v_mad_i32_i24 v5, s17, v207, v5
	v_ashrrev_i32_e32 v13, 31, v12
	v_lshl_add_u64 v[4:5], v[4:5], 0, s[38:39]
	v_lshlrev_b64 v[12:13], 7, v[12:13]
	v_lshl_add_u64 v[8:9], v[4:5], 0, v[60:61]
	v_lshl_add_u64 v[16:17], v[44:45], 0, v[12:13]
	v_lshl_add_u64 v[66:67], v[46:47], 0, v[12:13]
	s_waitcnt vmcnt(6)
; #define LAS __attribute__((address_space(3)))
; __device__ __forceinline__ void retkv_item(const bf16_t* hbuf, const float* rot, float* kvbuf, LAS bf16_t* wl, int item, int lane) {
;     ...
;     { const int cr = lane >> 3, dc = lane & 7, fc = dc & 3;
; #pragma unroll
;       for (int i = 0; i < 8; ++i) { const int row = cr + 8 * i; const bf16_t* kp = hbuf + (t0 + row) * INWP + C_RK + h * 64;
;           const u32x4 x1 = *(const u32x4*)(kp + 8 * fc), x2 = *(const u32x4*)(kp + 32 + 8 * fc);
;           const int pos = n * 64 + row; u32x4 o1, o2;
;           rot8(x1, x2, rot + (size_t)pos * 32 + 8 * fc, rot + 16384 * 32 + (size_t)pos * 32 + 8 * fc, 0.125f, o1, o2);
;           const u32x4 w = dc < 4 ? o1 : o2;
;           LAS bf16_t* t = kT + (8 * dc) * TLD + row;
;           t[0 * TLD] = (bf16_t)(w.x & 0xffff); t[1 * TLD] = (bf16_t)(w.x >> 16); t[2 * TLD] = (bf16_t)(w.y & 0xffff); t[3 * TLD] = (bf16_t)(w.y >> 16);
;           t[4 * TLD] = (bf16_t)(w.z & 0xffff); t[5 * TLD] = (bf16_t)(w.z >> 16); t[6 * TLD] = (bf16_t)(w.w & 0xffff); t[7 * TLD] = (bf16_t)(w.w >> 16); } }
	v_mov_b64_e32 v[4:5], v[92:93]
	v_mov_b64_e32 v[6:7], v[94:95]
	v_mov_b64_e32 v[8:9], v[96:97]
	v_mov_b64_e32 v[10:11], v[98:99]
	v_mov_b64_e32 v[12:13], v[100:101]
	v_mov_b64_e32 v[14:15], v[102:103]
	v_mov_b64_e32 v[16:17], v[104:105]
	v_mov_b64_e32 v[18:19], v[106:107]
	v_mov_b64_e32 v[20:21], v[108:109]
	v_mov_b64_e32 v[22:23], v[110:111]
	v_mov_b64_e32 v[66:67], v[112:113]
	v_mov_b64_e32 v[68:69], v[114:115]
	v_lshlrev_b32_e32 v71, 16, v4
	v_lshlrev_b32_e32 v70, 16, v8
	v_mov_b32_e32 v72, v66
	v_mov_b32_e32 v73, v16
	v_pk_mul_f32 v[72:73], v[72:73], v[70:71]
	s_nop 0
	v_sub_f32_e32 v1, v73, v72
	v_mov_b32_e32 v72, v16
	v_mov_b32_e32 v73, v66
	v_pk_mul_f32 v[70:71], v[72:73], v[70:71]
	v_mov_b32_e32 v66, v17
	v_add_f32_e32 v16, v70, v71
	v_mul_f32_e32 v51, 0x3e000000, v16
	v_and_b32_e32 v71, 0xffff0000, v4
	v_and_b32_e32 v70, 0xffff0000, v8
	v_mov_b32_e32 v16, v67
	v_pk_mul_f32 v[72:73], v[16:17], v[70:71]
	v_pk_mul_f32 v[16:17], v[66:67], v[70:71]
	v_sub_f32_e32 v4, v73, v72
	v_mul_f32_e32 v53, 0x3e000000, v4
	v_add_f32_e32 v4, v16, v17
	v_lshlrev_b32_e32 v17, 16, v5
	v_lshlrev_b32_e32 v16, 16, v9
	v_mov_b32_e32 v66, v68
	v_mov_b32_e32 v67, v18
	v_pk_mul_f32 v[66:67], v[66:67], v[16:17]
	v_mul_f32_e32 v55, 0x3e000000, v4
	v_sub_f32_e32 v4, v67, v66
	v_mov_b32_e32 v66, v18
	v_mov_b32_e32 v67, v68
	v_pk_mul_f32 v[16:17], v[66:67], v[16:17]
	v_mul_f32_e32 v57, 0x3e000000, v4
	v_add_f32_e32 v4, v16, v17
	v_mul_f32_e32 v16, 0x3e000000, v4
	v_and_b32_e32 v5, 0xffff0000, v5
	v_and_b32_e32 v4, 0xffff0000, v9
	v_mov_b32_e32 v18, v69
	v_mov_b32_e32 v68, v19
	v_pk_mul_f32 v[8:9], v[18:19], v[4:5]
	v_pk_mul_f32 v[4:5], v[68:69], v[4:5]
	v_sub_f32_e32 v8, v9, v8
	v_add_f32_e32 v4, v4, v5
	v_mul_f32_e32 v17, 0x3e000000, v8
	v_mul_f32_e32 v18, 0x3e000000, v4
	v_lshlrev_b32_e32 v5, 16, v6
	v_lshlrev_b32_e32 v4, 16, v10
	v_mov_b32_e32 v8, v20
	v_mov_b32_e32 v9, v12
	v_pk_mul_f32 v[8:9], v[8:9], v[4:5]
	v_mul_f32_e32 v1, 0x3e000000, v1
	v_sub_f32_e32 v8, v9, v8
	v_mul_f32_e32 v19, 0x3e000000, v8
	v_mov_b32_e32 v8, v12
	v_mov_b32_e32 v9, v20
	v_pk_mul_f32 v[4:5], v[8:9], v[4:5]
	v_mov_b32_e32 v12, v21
	v_add_f32_e32 v4, v4, v5
	v_mul_f32_e32 v59, 0x3e000000, v4
	v_and_b32_e32 v5, 0xffff0000, v6
	v_and_b32_e32 v4, 0xffff0000, v10
	v_mov_b32_e32 v20, v13
	v_pk_mul_f32 v[8:9], v[12:13], v[4:5]
	v_pk_mul_f32 v[4:5], v[20:21], v[4:5]
	v_sub_f32_e32 v6, v9, v8
	v_add_f32_e32 v4, v4, v5
	v_mul_f32_e32 v12, 0x3e000000, v4
	v_lshlrev_b32_e32 v5, 16, v7
	v_lshlrev_b32_e32 v4, 16, v11
	v_mov_b32_e32 v8, v22
	v_mov_b32_e32 v9, v14
	v_pk_mul_f32 v[8:9], v[8:9], v[4:5]
	v_mul_f32_e32 v10, 0x3e000000, v6
	v_sub_f32_e32 v6, v9, v8
	v_mov_b32_e32 v8, v14
	v_mov_b32_e32 v9, v22
	v_pk_mul_f32 v[4:5], v[8:9], v[4:5]
	v_mov_b32_e32 v14, v23
	v_add_f32_e32 v4, v4, v5
	v_mul_f32_e32 v8, 0x3e000000, v4
	v_and_b32_e32 v5, 0xffff0000, v7
	v_and_b32_e32 v4, 0xffff0000, v11
	v_mov_b32_e32 v22, v15
	v_mul_f32_e32 v13, 0x3e000000, v6
	v_pk_mul_f32 v[6:7], v[14:15], v[4:5]
	v_pk_mul_f32 v[4:5], v[22:23], v[4:5]
	v_sub_f32_e32 v6, v7, v6
	v_add_f32_e32 v4, v4, v5
	v_mul_f32_e32 v6, 0x3e000000, v6
	v_mul_f32_e32 v4, 0x3e000000, v4
	v_cvt_pk_bf16_f32 v1, v1, v53
	v_cvt_pk_bf16_f32 v5, v57, v17
	v_cvt_pk_bf16_f32 v6, v13, v6
	v_cvt_pk_bf16_f32 v9, v51, v55
	v_cvt_pk_bf16_f32 v4, v8, v4
	v_cvt_pk_bf16_f32 v7, v19, v10
	v_cvt_pk_bf16_f32 v10, v16, v18
	v_cvt_pk_bf16_f32 v11, v59, v12
	v_add_u32_e32 v12, -8, v0
	v_cndmask_b32_e32 v1, v9, v1, vcc
	v_cndmask_b32_e32 v4, v4, v6, vcc
	v_cndmask_b32_e32 v6, v11, v7, vcc
	v_cndmask_b32_e32 v5, v10, v5, vcc
	ds_write_b16 v29, v1 offset:80
	ds_write_b16_d16_hi v29, v1 offset:224
	ds_write_b16 v29, v5 offset:368
	ds_write_b16_d16_hi v29, v5 offset:512
	ds_write_b16 v29, v6 offset:656
	ds_write_b16_d16_hi v29, v6 offset:800
	ds_write_b16 v29, v4 offset:944
	ds_write_b16_d16_hi v29, v4 offset:1088
	v_or_b32_e32 v1, s20, v40
	v_mad_u64_u32 v[4:5], s[0:1], v1, s5, v[2:3]
	v_mad_i32_i24 v5, s17, v207, v5
	v_ashrrev_i32_e32 v13, 31, v12
	v_lshl_add_u64 v[4:5], v[4:5], 0, s[38:39]
	v_lshlrev_b64 v[12:13], 7, v[12:13]
	v_lshl_add_u64 v[8:9], v[4:5], 0, v[60:61]
	v_lshl_add_u64 v[16:17], v[44:45], 0, v[12:13]
	v_lshl_add_u64 v[66:67], v[46:47], 0, v[12:13]
	s_waitcnt vmcnt(0)
; #define LAS __attribute__((address_space(3)))
; __device__ __forceinline__ void lds_fence() { asm volatile("s_waitcnt lgkmcnt(0)" ::: "memory"); }
; __device__ __forceinline__ void retkv_item(const bf16_t* hbuf, const float* rot, float* kvbuf, LAS bf16_t* wl, int item, int lane) {
;     ...
;     { const int cr = lane >> 3, dc = lane & 7, fc = dc & 3;
; #pragma unroll
;       for (int i = 0; i < 8; ++i) { const int row = cr + 8 * i; const bf16_t* kp = hbuf + (t0 + row) * INWP + C_RK + h * 64;
;           const u32x4 x1 = *(const u32x4*)(kp + 8 * fc), x2 = *(const u32x4*)(kp + 32 + 8 * fc);
;           const int pos = n * 64 + row; u32x4 o1, o2;
;           rot8(x1, x2, rot + (size_t)pos * 32 + 8 * fc, rot + 16384 * 32 + (size_t)pos * 32 + 8 * fc, 0.125f, o1, o2);
;           const u32x4 w = dc < 4 ? o1 : o2;
;           LAS bf16_t* t = kT + (8 * dc) * TLD + row;
;           t[0 * TLD] = (bf16_t)(w.x & 0xffff); t[1 * TLD] = (bf16_t)(w.x >> 16); t[2 * TLD] = (bf16_t)(w.y & 0xffff); t[3 * TLD] = (bf16_t)(w.y >> 16);
;           t[4 * TLD] = (bf16_t)(w.z & 0xffff); t[5 * TLD] = (bf16_t)(w.z >> 16); t[6 * TLD] = (bf16_t)(w.w & 0xffff); t[7 * TLD] = (bf16_t)(w.w >> 16); } }
;     lds_fence();
;     const int r = lane & 15, q = lane >> 4;
;     float* outp = kvbuf + (size_t)item * 4096;
	v_mov_b64_e32 v[4:5], v[116:117]
	v_mov_b64_e32 v[6:7], v[118:119]
	v_mov_b64_e32 v[8:9], v[120:121]
	v_mov_b64_e32 v[10:11], v[122:123]
	v_mov_b64_e32 v[12:13], v[124:125]
	v_mov_b64_e32 v[14:15], v[126:127]
	v_mov_b64_e32 v[16:17], v[128:129]
	v_mov_b64_e32 v[18:19], v[130:131]
	v_mov_b64_e32 v[20:21], v[132:133]
	v_mov_b64_e32 v[22:23], v[134:135]
	v_mov_b64_e32 v[66:67], v[136:137]
	v_mov_b64_e32 v[68:69], v[138:139]
	v_lshlrev_b32_e32 v71, 16, v4
	v_lshlrev_b32_e32 v70, 16, v8
	v_mov_b32_e32 v72, v66
	v_mov_b32_e32 v73, v16
	v_pk_mul_f32 v[72:73], v[72:73], v[70:71]
	s_nop 0
	v_sub_f32_e32 v1, v73, v72
	v_mov_b32_e32 v72, v16
	v_mov_b32_e32 v73, v66
	v_pk_mul_f32 v[70:71], v[72:73], v[70:71]
	v_mov_b32_e32 v66, v17
	v_add_f32_e32 v16, v70, v71
	v_mul_f32_e32 v51, 0x3e000000, v16
	v_and_b32_e32 v71, 0xffff0000, v4
	v_and_b32_e32 v70, 0xffff0000, v8
	v_mov_b32_e32 v16, v67
	v_pk_mul_f32 v[72:73], v[16:17], v[70:71]
	v_pk_mul_f32 v[16:17], v[66:67], v[70:71]
	v_sub_f32_e32 v4, v73, v72
	v_mul_f32_e32 v53, 0x3e000000, v4
	v_add_f32_e32 v4, v16, v17
	v_lshlrev_b32_e32 v17, 16, v5
	v_lshlrev_b32_e32 v16, 16, v9
	v_mov_b32_e32 v66, v68
	v_mov_b32_e32 v67, v18
	v_pk_mul_f32 v[66:67], v[66:67], v[16:17]
	v_mul_f32_e32 v55, 0x3e000000, v4
	v_sub_f32_e32 v4, v67, v66
	v_mov_b32_e32 v66, v18
	v_mov_b32_e32 v67, v68
	v_pk_mul_f32 v[16:17], v[66:67], v[16:17]
	v_mul_f32_e32 v57, 0x3e000000, v4
	v_add_f32_e32 v4, v16, v17
	v_mul_f32_e32 v16, 0x3e000000, v4
	v_and_b32_e32 v5, 0xffff0000, v5
	v_and_b32_e32 v4, 0xffff0000, v9
	v_mov_b32_e32 v18, v69
	v_mov_b32_e32 v68, v19
	v_pk_mul_f32 v[8:9], v[18:19], v[4:5]
	v_pk_mul_f32 v[4:5], v[68:69], v[4:5]
	v_sub_f32_e32 v8, v9, v8
	v_add_f32_e32 v4, v4, v5
	v_mul_f32_e32 v17, 0x3e000000, v8
	v_mul_f32_e32 v18, 0x3e000000, v4
	v_lshlrev_b32_e32 v5, 16, v6
	v_lshlrev_b32_e32 v4, 16, v10
	v_mov_b32_e32 v8, v20
	v_mov_b32_e32 v9, v12
	v_pk_mul_f32 v[8:9], v[8:9], v[4:5]
	v_mul_f32_e32 v1, 0x3e000000, v1
	v_sub_f32_e32 v8, v9, v8
	v_mul_f32_e32 v19, 0x3e000000, v8
	v_mov_b32_e32 v8, v12
	v_mov_b32_e32 v9, v20
	v_pk_mul_f32 v[4:5], v[8:9], v[4:5]
	v_mov_b32_e32 v12, v21
	v_add_f32_e32 v4, v4, v5
	v_mul_f32_e32 v59, 0x3e000000, v4
	v_and_b32_e32 v5, 0xffff0000, v6
	v_and_b32_e32 v4, 0xffff0000, v10
	v_mov_b32_e32 v20, v13
	v_pk_mul_f32 v[8:9], v[12:13], v[4:5]
	v_pk_mul_f32 v[4:5], v[20:21], v[4:5]
	v_sub_f32_e32 v6, v9, v8
	v_add_f32_e32 v4, v4, v5
	v_mul_f32_e32 v12, 0x3e000000, v4
	v_lshlrev_b32_e32 v5, 16, v7
	v_lshlrev_b32_e32 v4, 16, v11
	v_mov_b32_e32 v8, v22
	v_mov_b32_e32 v9, v14
	v_pk_mul_f32 v[8:9], v[8:9], v[4:5]
	v_mul_f32_e32 v10, 0x3e000000, v6
	v_sub_f32_e32 v6, v9, v8
	v_mov_b32_e32 v8, v14
	v_mov_b32_e32 v9, v22
	v_pk_mul_f32 v[4:5], v[8:9], v[4:5]
	v_mov_b32_e32 v14, v23
	v_add_f32_e32 v4, v4, v5
	v_mul_f32_e32 v8, 0x3e000000, v4
	v_and_b32_e32 v5, 0xffff0000, v7
	v_and_b32_e32 v4, 0xffff0000, v11
	v_mov_b32_e32 v22, v15
	v_mul_f32_e32 v13, 0x3e000000, v6
	v_pk_mul_f32 v[6:7], v[14:15], v[4:5]
	v_pk_mul_f32 v[4:5], v[22:23], v[4:5]
	v_sub_f32_e32 v6, v7, v6
	v_add_f32_e32 v4, v4, v5
	v_mul_f32_e32 v6, 0x3e000000, v6
	v_mul_f32_e32 v4, 0x3e000000, v4
	v_cvt_pk_bf16_f32 v1, v1, v53
	v_cvt_pk_bf16_f32 v5, v57, v17
	v_cvt_pk_bf16_f32 v6, v13, v6
	v_cvt_pk_bf16_f32 v9, v51, v55
	v_cvt_pk_bf16_f32 v4, v8, v4
	v_cvt_pk_bf16_f32 v7, v19, v10
	v_cvt_pk_bf16_f32 v10, v16, v18
	v_cvt_pk_bf16_f32 v11, v59, v12
	s_nop 0
	v_cndmask_b32_e32 v1, v9, v1, vcc
	v_cndmask_b32_e32 v4, v4, v6, vcc
	v_cndmask_b32_e32 v6, v11, v7, vcc
	v_cndmask_b32_e32 v5, v10, v5, vcc
	ds_write_b16 v29, v1 offset:96
	ds_write_b16_d16_hi v29, v1 offset:240
	ds_write_b16 v29, v5 offset:384
	ds_write_b16_d16_hi v29, v5 offset:528
	ds_write_b16 v29, v6 offset:672
	ds_write_b16_d16_hi v29, v6 offset:816
	ds_write_b16 v29, v4 offset:960
	ds_write_b16_d16_hi v29, v4 offset:1104
	v_or_b32_e32 v1, s20, v42
	v_mad_u64_u32 v[2:3], s[0:1], v1, s5, v[2:3]
	v_mad_i32_i24 v3, s17, v207, v3
	v_lshl_add_u64 v[2:3], v[2:3], 0, s[38:39]
	v_ashrrev_i32_e32 v1, 31, v0
	v_lshl_add_u64 v[2:3], v[2:3], 0, v[60:61]
	v_lshlrev_b64 v[0:1], 7, v[0:1]
	global_load_dwordx4 v[8:11], v[2:3], off offset:3584
	global_load_dwordx4 v[12:15], v[2:3], off offset:3648
	v_lshl_add_u64 v[2:3], v[44:45], 0, v[0:1]
	v_lshl_add_u64 v[20:21], v[46:47], 0, v[0:1]
	global_load_dwordx4 v[4:7], v[2:3], off offset:16
	global_load_dwordx4 v[16:19], v[2:3], off
	s_nop 0
	global_load_dwordx4 v[0:3], v[20:21], off offset:16
	s_nop 0
	global_load_dwordx4 v[20:23], v[20:21], off
	s_lshl_b64 s[0:1], s[36:37], 14
	v_lshl_add_u64 v[86:87], v[48:49], 0, s[0:1]
	v_add_co_u32_e64 v88, s[0:1], s45, v86
	s_add_i32 s36, s36, s14
	s_nop 0
	v_addc_co_u32_e64 v89, s[0:1], 0, v87, s[0:1]
	v_add_co_u32_e64 v90, s[0:1], s27, v86
	s_cmpk_gt_i32 s36, 0xbff
	s_nop 0
	v_addc_co_u32_e64 v91, s[0:1], 0, v87, s[0:1]
	s_waitcnt vmcnt(5)
	v_lshlrev_b32_e32 v67, 16, v8
	s_waitcnt vmcnt(4)
	v_lshlrev_b32_e32 v66, 16, v12
	s_waitcnt vmcnt(2)
	v_mov_b32_e32 v69, v16
	s_waitcnt vmcnt(0)
; #define LAS __attribute__((address_space(3)))
; __device__ __forceinline__ void lds_fence() { asm volatile("s_waitcnt lgkmcnt(0)" ::: "memory"); }
; __device__ __forceinline__ void retkv_item(const bf16_t* hbuf, const float* rot, float* kvbuf, LAS bf16_t* wl, int item, int lane) {
;     ...
;           const u32x4 w = dc < 4 ? o1 : o2;
;           LAS bf16_t* t = kT + (8 * dc) * TLD + row;
;           t[0 * TLD] = (bf16_t)(w.x & 0xffff); t[1 * TLD] = (bf16_t)(w.x >> 16); t[2 * TLD] = (bf16_t)(w.y & 0xffff); t[3 * TLD] = (bf16_t)(w.y >> 16);
;           t[4 * TLD] = (bf16_t)(w.z & 0xffff); t[5 * TLD] = (bf16_t)(w.z >> 16); t[6 * TLD] = (bf16_t)(w.w & 0xffff); t[7 * TLD] = (bf16_t)(w.w >> 16); } }
;     lds_fence();
;     const int r = lane & 15, q = lane >> 4;
;     float* outp = kvbuf + (size_t)item * 4096;
; #pragma unroll
;     for (int et = 0; et < 4; ++et) {
;         bf16x8 vf[2];
; #pragma unroll
;         for (int ks = 0; ks < 2; ++ks) vf[ks] = *(const LAS bf16x8*)(vT + (16 * et + r) * TLD + 32 * ks + 8 * q);
; #pragma unroll
;         for (int dt = 0; dt < 4; ++dt) { f32x4 acc = {0.f, 0.f, 0.f, 0.f};
; #pragma unroll
;             for (int ks = 0; ks < 2; ++ks) { const bf16x8 kf = *(const LAS bf16x8*)(kT + (16 * dt + r) * TLD + 32 * ks + 8 * q);
;                 acc = __builtin_amdgcn_mfma_f32_16x16x32_bf16(kf, vf[ks], acc, 0, 0, 0); }
;             *(f32x4*)(outp + (16 * et + r) * 64 + 16 * dt + 4 * q) = acc; } }
	v_mov_b32_e32 v68, v20
	v_pk_mul_f32 v[68:69], v[68:69], v[66:67]
	s_nop 0
	v_sub_f32_e32 v51, v69, v68
	v_mov_b32_e32 v68, v16
	v_mov_b32_e32 v69, v20
	v_pk_mul_f32 v[66:67], v[68:69], v[66:67]
	v_mov_b32_e32 v20, v17
	v_add_f32_e32 v16, v66, v67
	v_mul_f32_e32 v53, 0x3e000000, v16
	v_and_b32_e32 v67, 0xffff0000, v8
	v_and_b32_e32 v66, 0xffff0000, v12
	v_mov_b32_e32 v16, v21
	v_pk_mul_f32 v[68:69], v[16:17], v[66:67]
	v_pk_mul_f32 v[16:17], v[20:21], v[66:67]
	v_lshlrev_b32_e32 v21, 16, v9
	v_add_f32_e32 v12, v16, v17
	v_lshlrev_b32_e32 v20, 16, v13
	v_mov_b32_e32 v16, v22
	v_mov_b32_e32 v17, v18
	v_mov_b32_e32 v66, v18
	v_mov_b32_e32 v67, v22
	v_pk_mul_f32 v[16:17], v[16:17], v[20:21]
	v_pk_mul_f32 v[20:21], v[66:67], v[20:21]
	v_sub_f32_e32 v16, v17, v16
	v_add_f32_e32 v17, v20, v21
	v_and_b32_e32 v21, 0xffff0000, v9
	v_and_b32_e32 v20, 0xffff0000, v13
	v_mov_b32_e32 v18, v23
	v_mov_b32_e32 v22, v19
	v_pk_mul_f32 v[66:67], v[18:19], v[20:21]
	v_pk_mul_f32 v[18:19], v[22:23], v[20:21]
	v_lshlrev_b32_e32 v21, 16, v10
	v_add_f32_e32 v13, v18, v19
	v_lshlrev_b32_e32 v20, 16, v14
	v_mov_b32_e32 v18, v0
	v_mov_b32_e32 v19, v4
	v_mov_b32_e32 v22, v4
	v_mov_b32_e32 v23, v0
	v_pk_mul_f32 v[18:19], v[18:19], v[20:21]
	v_pk_mul_f32 v[20:21], v[22:23], v[20:21]
	v_mov_b32_e32 v4, v1
	v_add_f32_e32 v0, v20, v21
	v_and_b32_e32 v21, 0xffff0000, v10
	v_and_b32_e32 v20, 0xffff0000, v14
	v_pk_mul_f32 v[22:23], v[4:5], v[20:21]
	v_sub_f32_e32 v18, v19, v18
	v_mul_f32_e32 v19, 0x3e000000, v0
	v_sub_f32_e32 v0, v23, v22
	v_mul_f32_e32 v4, 0x3e000000, v0
	v_mov_b32_e32 v0, v5
	v_pk_mul_f32 v[0:1], v[0:1], v[20:21]
	v_mov_b32_e32 v20, v2
	v_add_f32_e32 v0, v0, v1
	v_mul_f32_e32 v5, 0x3e000000, v0
	v_lshlrev_b32_e32 v1, 16, v11
	v_lshlrev_b32_e32 v0, 16, v15
	v_mov_b32_e32 v21, v6
	v_pk_mul_f32 v[20:21], v[20:21], v[0:1]
	v_sub_f32_e32 v8, v69, v68
	v_sub_f32_e32 v10, v21, v20
	v_mov_b32_e32 v20, v6
	v_mov_b32_e32 v21, v2
	v_pk_mul_f32 v[0:1], v[20:21], v[0:1]
	v_mov_b32_e32 v6, v3
	v_add_f32_e32 v0, v0, v1
	v_mul_f32_e32 v14, 0x3e000000, v0
	v_and_b32_e32 v1, 0xffff0000, v11
	v_and_b32_e32 v0, 0xffff0000, v15
	v_pk_mul_f32 v[20:21], v[6:7], v[0:1]
	v_mul_f32_e32 v51, 0x3e000000, v51
	v_sub_f32_e32 v2, v21, v20
	v_mul_f32_e32 v6, 0x3e000000, v2
	v_mov_b32_e32 v2, v7
	v_pk_mul_f32 v[0:1], v[2:3], v[0:1]
	v_mul_f32_e32 v8, 0x3e000000, v8
	v_add_f32_e32 v0, v0, v1
	v_sub_f32_e32 v9, v67, v66
	v_mul_f32_e32 v0, 0x3e000000, v0
	v_cvt_pk_bf16_f32 v1, v51, v8
	v_mul_f32_e32 v12, 0x3e000000, v12
	v_mul_f32_e32 v16, 0x3e000000, v16
	v_mul_f32_e32 v9, 0x3e000000, v9
	v_mul_f32_e32 v18, 0x3e000000, v18
	v_mul_f32_e32 v10, 0x3e000000, v10
	v_cvt_pk_bf16_f32 v2, v16, v9
	v_cvt_pk_bf16_f32 v3, v18, v4
	v_cvt_pk_bf16_f32 v4, v10, v6
	v_cvt_pk_bf16_f32 v6, v53, v12
	v_cvt_pk_bf16_f32 v0, v14, v0
	v_mul_f32_e32 v17, 0x3e000000, v17
	v_cndmask_b32_e32 v1, v6, v1, vcc
	v_mul_f32_e32 v13, 0x3e000000, v13
	v_cvt_pk_bf16_f32 v7, v17, v13
	v_cvt_pk_bf16_f32 v5, v19, v5
	v_cndmask_b32_e32 v0, v0, v4, vcc
	v_cndmask_b32_e32 v3, v5, v3, vcc
	v_cndmask_b32_e32 v2, v7, v2, vcc
	ds_write_b16 v29, v1 offset:112
	ds_write_b16_d16_hi v29, v1 offset:256
	ds_write_b16 v29, v2 offset:400
	ds_write_b16_d16_hi v29, v2 offset:544
	ds_write_b16 v29, v3 offset:688
	ds_write_b16_d16_hi v29, v3 offset:832
	ds_write_b16 v29, v0 offset:976
	ds_write_b16_d16_hi v29, v0 offset:1120
	s_waitcnt lgkmcnt(0)
	ds_read_b128 v[0:3], v64 offset:9216
	ds_read_b128 v[4:7], v64 offset:9280
	ds_read_b128 v[8:11], v64
	ds_read_b128 v[16:19], v64 offset:64
	s_waitcnt lgkmcnt(1)
	v_mfma_f32_16x16x32_bf16 v[12:15], v[8:11], v[0:3], 0
	ds_read_b128 v[66:69], v64 offset:2368
	ds_read_b128 v[74:77], v64 offset:4672
	s_waitcnt lgkmcnt(2)
	v_mfma_f32_16x16x32_bf16 v[12:15], v[16:19], v[4:7], v[12:15]
	s_nop 7
	global_store_dwordx4 v[86:87], v[12:15], off
	ds_read_b128 v[12:15], v64 offset:2304
	s_waitcnt lgkmcnt(0)
; #define LAS __attribute__((address_space(3)))
; __device__ __forceinline__ void lds_fence() { asm volatile("s_waitcnt lgkmcnt(0)" ::: "memory"); }
; __device__ __forceinline__ void retkv_item(const bf16_t* hbuf, const float* rot, float* kvbuf, LAS bf16_t* wl, int item, int lane) {
;     ...
; #pragma unroll
;     for (int et = 0; et < 4; ++et) {
;         bf16x8 vf[2];
; #pragma unroll
;         for (int ks = 0; ks < 2; ++ks) vf[ks] = *(const LAS bf16x8*)(vT + (16 * et + r) * TLD + 32 * ks + 8 * q);
; #pragma unroll
;         for (int dt = 0; dt < 4; ++dt) { f32x4 acc = {0.f, 0.f, 0.f, 0.f};
; #pragma unroll
;             for (int ks = 0; ks < 2; ++ks) { const bf16x8 kf = *(const LAS bf16x8*)(kT + (16 * dt + r) * TLD + 32 * ks + 8 * q);
;                 acc = __builtin_amdgcn_mfma_f32_16x16x32_bf16(kf, vf[ks], acc, 0, 0, 0); }
;             *(f32x4*)(outp + (16 * et + r) * 64 + 16 * dt + 4 * q) = acc; } }
;     lds_fence();
	v_mfma_f32_16x16x32_bf16 v[20:23], v[12:15], v[0:3], 0
	v_mfma_f32_16x16x32_bf16 v[20:23], v[66:69], v[4:7], v[20:23]
	s_nop 7
	global_store_dwordx4 v[86:87], v[20:23], off offset:64
	ds_read_b128 v[20:23], v64 offset:4608
	s_waitcnt lgkmcnt(0)
	v_mfma_f32_16x16x32_bf16 v[70:73], v[20:23], v[0:3], 0
	v_mfma_f32_16x16x32_bf16 v[70:73], v[74:77], v[4:7], v[70:73]
	s_nop 7
	global_store_dwordx4 v[86:87], v[70:73], off offset:128
	ds_read_b128 v[70:73], v65
	s_waitcnt lgkmcnt(0)
	v_mfma_f32_16x16x32_bf16 v[78:81], v[70:73], v[0:3], 0
	ds_read_b128 v[0:3], v65 offset:64
	s_waitcnt lgkmcnt(0)
	v_mfma_f32_16x16x32_bf16 v[4:7], v[0:3], v[4:7], v[78:81]
	s_nop 7
	global_store_dwordx4 v[86:87], v[4:7], off offset:192
	ds_read_b128 v[4:7], v64 offset:11520
	ds_read_b128 v[78:81], v64 offset:11584
	s_waitcnt lgkmcnt(1)
	v_mfma_f32_16x16x32_bf16 v[82:85], v[8:11], v[4:7], 0
	s_waitcnt lgkmcnt(0)
	v_mfma_f32_16x16x32_bf16 v[82:85], v[16:19], v[78:81], v[82:85]
	s_nop 7
	global_store_dwordx4 v[90:91], v[82:85], off offset:-4096
	s_nop 1
	v_mfma_f32_16x16x32_bf16 v[82:85], v[12:15], v[4:7], 0
	v_mfma_f32_16x16x32_bf16 v[82:85], v[66:69], v[78:81], v[82:85]
	s_nop 7
	global_store_dwordx4 v[88:89], v[82:85], off offset:64
	s_nop 1
	v_mfma_f32_16x16x32_bf16 v[82:85], v[20:23], v[4:7], 0
	v_mfma_f32_16x16x32_bf16 v[4:7], v[70:73], v[4:7], 0
	v_mfma_f32_16x16x32_bf16 v[82:85], v[74:77], v[78:81], v[82:85]
	v_mfma_f32_16x16x32_bf16 v[4:7], v[0:3], v[78:81], v[4:7]
	s_nop 6
	global_store_dwordx4 v[88:89], v[82:85], off offset:128
	global_store_dwordx4 v[88:89], v[4:7], off offset:192
	ds_read_b128 v[4:7], v64 offset:13824
	ds_read_b128 v[78:81], v64 offset:13888
	s_waitcnt lgkmcnt(1)
	v_mfma_f32_16x16x32_bf16 v[82:85], v[8:11], v[4:7], 0
	s_waitcnt lgkmcnt(0)
	v_mfma_f32_16x16x32_bf16 v[82:85], v[16:19], v[78:81], v[82:85]
	s_nop 7
	global_store_dwordx4 v[90:91], v[82:85], off
	s_nop 1
	v_mfma_f32_16x16x32_bf16 v[82:85], v[12:15], v[4:7], 0
	v_mfma_f32_16x16x32_bf16 v[82:85], v[66:69], v[78:81], v[82:85]
	s_nop 7
	global_store_dwordx4 v[90:91], v[82:85], off offset:64
	s_nop 1
	v_mfma_f32_16x16x32_bf16 v[82:85], v[20:23], v[4:7], 0
	v_mfma_f32_16x16x32_bf16 v[4:7], v[70:73], v[4:7], 0
	v_mfma_f32_16x16x32_bf16 v[82:85], v[74:77], v[78:81], v[82:85]
	v_mfma_f32_16x16x32_bf16 v[4:7], v[0:3], v[78:81], v[4:7]
	s_nop 6
	global_store_dwordx4 v[90:91], v[82:85], off offset:128
	global_store_dwordx4 v[90:91], v[4:7], off offset:192
	ds_read_b128 v[4:7], v65 offset:9216
	ds_read_b128 v[78:81], v65 offset:9280
	s_waitcnt lgkmcnt(1)
	v_mfma_f32_16x16x32_bf16 v[8:11], v[8:11], v[4:7], 0
	s_waitcnt lgkmcnt(0)
	v_mfma_f32_16x16x32_bf16 v[8:11], v[16:19], v[78:81], v[8:11]
	v_add_co_u32_e64 v16, s[0:1], s46, v86
	s_nop 1
	v_addc_co_u32_e64 v17, s[0:1], 0, v87, s[0:1]
	s_nop 3
	global_store_dwordx4 v[16:17], v[8:11], off
	s_nop 1
	v_mfma_f32_16x16x32_bf16 v[8:11], v[12:15], v[4:7], 0
	v_mfma_f32_16x16x32_bf16 v[8:11], v[66:69], v[78:81], v[8:11]
	s_nop 7
	global_store_dwordx4 v[16:17], v[8:11], off offset:64
	s_nop 1
	v_mfma_f32_16x16x32_bf16 v[8:11], v[20:23], v[4:7], 0
	v_mfma_f32_16x16x32_bf16 v[4:7], v[70:73], v[4:7], 0
	v_mfma_f32_16x16x32_bf16 v[8:11], v[74:77], v[78:81], v[8:11]
	v_mfma_f32_16x16x32_bf16 v[0:3], v[0:3], v[78:81], v[4:7]
	s_nop 6
	global_store_dwordx4 v[16:17], v[8:11], off offset:128
	global_store_dwordx4 v[16:17], v[0:3], off offset:192
	s_waitcnt lgkmcnt(0)
	s_cbranch_scc0 .LBB0_341
	s_nop 0
	v_and_b32_e32 v0, 56, v27
	v_lshlrev_b32_e32 v1, 2, v248
	s_mov_b32 s38, 0x24000
	s_mov_b32 s37, 0xc000
	s_mov_b32 s36, 0x18000
	v_xor_b32_e32 v4, 4, v1
	v_xor_b32_e32 v5, 8, v1
	v_xor_b32_e32 v6, 16, v1
	v_xor_b32_e32 v7, 32, v1
	v_xor_b32_e32 v8, 64, v1
	v_xor_b32_e32 v9, 0x80, v1
	v_cmp_eq_u32_e32 vcc, 0, v248
	v_lshlrev_b32_e32 v32, 1, v0
	s_mov_b32 s12, s16
	s_branch .LBB0_344
